# attention phase hand-written: S^T=KQ^T with -m as MFMA SrcC, threshold (2^8) re-referencing of the running max, permlane32 swaps, dwordx4 output stores
# speedup vs baseline: 1.0239x; 1.0128x over previous
.LBB0_327:
	s_andn2_b64 vcc, exec, s[4:5]
	s_cbranch_vccnz .LBB0_800
	s_cmp_lt_i32 s96, 1
	s_mov_b64 s[4:5], -1
	s_cbranch_scc1 .LBB0_384
	s_cmp_eq_u32 s96, 1
	s_cbranch_scc0 .LBB0_383
	v_readlane_b32 s4, v253, 18
	v_mov_b32_e32 v1, v175
	v_readlane_b32 s5, v253, 19
	s_andn2_b64 vcc, exec, s[4:5]
	v_readfirstlane_b32 s3, v1
	s_cbranch_vccnz .LBB0_383
	v_writelane_b32 v255, s96, 7
	v_writelane_b32 v255, s97, 8
	v_writelane_b32 v255, s98, 9
	v_writelane_b32 v255, s99, 10
	v_writelane_b32 v255, s86, 0
	v_writelane_b32 v255, s87, 1
	v_writelane_b32 v255, s42, 11
	s_mov_b32 s5, 0
	v_lshrrev_b32_e32 v212, 6, v175
	s_lshl_b32 s4, s42, 8
	v_writelane_b32 v255, s5, 12
	v_readfirstlane_b32 s3, v212
	v_readlane_b32 s48, v254, 20
	v_readlane_b32 s49, v254, 21
	v_readlane_b32 s46, v254, 22
	v_readlane_b32 s47, v254, 23
	v_readlane_b32 s50, v254, 12
	v_readlane_b32 s51, v254, 13
	v_readlane_b32 s59, v253, 3
	s_mov_b32 s52, s31
	s_nop 3
	s_add_u32 s48, s48, s4
	s_addc_u32 s49, s49, 0
	s_add_u32 s46, s46, s4
	s_addc_u32 s47, s47, 0
	s_lshr_b32 s4, s4, 2
	s_add_u32 s50, s50, s4
	s_addc_u32 s51, s51, 0
	s_lshr_b32 s71, s3, 1
	s_and_b32 s70, s3, 1
	s_lshl_b32 s70, s70, 6
	s_movk_i32 s60, 0xc00
	v_and_b32_e32 v1, 31, v175
	v_bfe_u32 v2, v175, 5, 1
	v_lshlrev_b32_e32 v3, 2, v2
	v_sub_u32_e32 v15, v1, v3
	v_cmp_eq_u32_e64 s[66:67], 1, v2
	v_and_b32_e32 v212, 7, v175
	v_cmp_gt_u32_e64 s[62:63], 2, v212
	v_cmp_eq_u32_e64 s[64:65], 0, v212
	v_lshlrev_b32_e32 v4, 4, v212
	v_lshrrev_b32_e32 v172, 3, v175
	v_mov_b32_e32 v216, 0x90
	v_mad_u32_u24 v5, v172, v216, v4
	v_add_u32_e32 v6, 0xd800, v5
	v_add_u32_e32 v7, 0xffffff80, v172
	v_add_u32_e32 v212, s70, v1
	v_lshlrev_b32_e32 v172, 4, v2
	v_mad_u32_u24 v8, v212, v216, v172
	v_bfe_u32 v172, v175, 2, 2
	v_add_u32_e32 v172, v172, v3
	v_add_u32_e32 v172, s70, v172
	v_bfe_u32 v217, v175, 4, 1
	v_lshlrev_b32_e32 v217, 5, v217
	v_and_b32_e32 v250, 3, v175
	v_lshl_add_u32 v217, v250, 3, v217
	v_mad_u32_u24 v9, v172, v216, v217
	v_add_u32_e32 v9, 0xd800, v9
	s_lshl_b32 s4, s71, 7
	v_lshlrev_b32_e32 v172, 4, v2
	v_add_u32_e32 v172, s4, v172
	v_mul_u32_u24_e32 v216, 0xc00, v212
	v_add_u32_e32 v10, v216, v172
	v_add_u32_e32 v11, 0x18000, v10
	v_lshlrev_b32_e32 v12, 6, v212
	v_lshlrev_b32_e32 v172, 4, v2
	v_add_u32_e32 v172, s4, v172
	v_lshl_add_u32 v13, v212, 11, v172
	v_add_u32_e32 v14, 0x10000, v13
	v_cndmask_b32_e64 v173, v10, v11, s[66:67]
	s_cmpk_lt_i32 s52, 0x400
	s_cbranch_scc0 .Lat_exit
.Lat_unit:
	s_and_b32 s54, s52, 3
	s_bfe_u32 s53, s52, 0x60002
	s_lshr_b32 s55, s52, 8
	s_lshl_b32 s4, s54, 2
	s_add_u32 s56, s4, s71
	s_lshl_b32 s5, s56, 2
	s_load_dword s11, s[50:51], s5
	s_cmp_eq_u32 s53, 0
	s_cselect_b32 s68, 128, 0
	s_movk_i32 s4, 0x100
	s_cmp_eq_u32 s53, 63
	s_cselect_b32 s69, s4, 0x180
	s_lshl_b32 s6, s55, 13
	s_lshl_b32 s7, s53, 7
	v_readlane_b32 s8, v254, 33
	v_readlane_b32 s9, v254, 34
	s_mul_i32 s10, s6, 0xc00
	s_lshl_b32 s13, s54, 7
	s_add_u32 s10, s10, s13
	s_nop 0
	s_add_u32 s38, s8, s10
	s_addc_u32 s39, s9, 0
	s_mul_i32 s10, s7, 0xc00
	s_lshl_b32 s13, s54, 9
	s_add_u32 s10, s10, s13
	s_lshl_b32 s13, s54, 7
	s_sub_u32 s10, s10, s13
	s_add_u32 s40, s38, s10
	s_addc_u32 s41, s39, 0
	s_add_u32 s42, s36, 0x180000
	s_addc_u32 s43, s37, 0
	s_lshl_b32 s10, s53, 13
	s_add_u32 s72, s42, s10
	s_addc_u32 s73, s43, 0
	v_readlane_b32 s8, v253, 20
	v_readlane_b32 s9, v253, 21
	s_add_u32 s10, s6, s7
	s_lshl_b32 s10, s10, 11
	s_lshl_b32 s13, s54, 9
	s_add_u32 s10, s10, s13
	s_add_u32 s44, s8, s10
	s_addc_u32 s45, s9, 0
	s_barrier
	global_load_dwordx4 v[96:99], v10, s[40:41] offset:0
	global_load_dwordx4 v[100:103], v10, s[40:41] offset:32
	global_load_dwordx4 v[104:107], v10, s[40:41] offset:64
	global_load_dwordx4 v[108:111], v10, s[40:41] offset:96
	global_load_dwordx4 v[238:241], v11, s[40:41] offset:0
	global_load_dwordx4 v[242:245], v11, s[40:41] offset:32
	global_load_dwordx4 v[246:249], v11, s[40:41] offset:64
	global_load_dwordx4 v[222:225], v11, s[40:41] offset:96
	v_lshlrev_b32_e32 v212, 1, v4
	global_load_dwordx4 v[64:67], v212, s[46:47]
	global_load_dwordx4 v[68:71], v212, s[46:47] offset:16
	v_add_u32_e32 v217, s7, v7
	v_add_u32_e32 v212, 0, v217
	v_max_i32_e32 v212, 0, v212
	v_min_u32_e32 v212, 0x1fff, v212
	v_mul_lo_u32 v172, v212, s60
	v_add_u32_e32 v172, v172, v4
	v_lshlrev_b32_e32 v216, 6, v212
	global_load_dwordx4 v[16:19], v172, s[38:39] offset:2048
	global_load_dwordx4 v[20:23], v172, s[38:39] offset:2560
	s_mov_b64 exec, s[62:63]
	global_load_dwordx4 v[116:119], v216, s[42:43] offset:0
	global_load_dwordx4 v[120:123], v216, s[42:43] offset:16
	global_load_dwordx4 v[124:127], v216, s[42:43] offset:32
	global_load_dwordx4 v[128:131], v216, s[42:43] offset:48
	s_mov_b64 exec, -1
	v_add_u32_e32 v212, 64, v217
	v_max_i32_e32 v212, 0, v212
	v_min_u32_e32 v212, 0x1fff, v212
	v_mul_lo_u32 v172, v212, s60
	v_add_u32_e32 v172, v172, v4
	v_lshlrev_b32_e32 v216, 6, v212
	global_load_dwordx4 v[24:27], v172, s[38:39] offset:2048
	global_load_dwordx4 v[28:31], v172, s[38:39] offset:2560
	s_mov_b64 exec, s[62:63]
	global_load_dwordx4 v[132:135], v216, s[42:43] offset:0
	global_load_dwordx4 v[136:139], v216, s[42:43] offset:16
	global_load_dwordx4 v[140:143], v216, s[42:43] offset:32
	global_load_dwordx4 v[144:147], v216, s[42:43] offset:48
	s_mov_b64 exec, -1
	v_add_u32_e32 v212, 128, v217
	v_max_i32_e32 v212, 0, v212
	v_min_u32_e32 v212, 0x1fff, v212
	v_mul_lo_u32 v172, v212, s60
	v_add_u32_e32 v172, v172, v4
	v_lshlrev_b32_e32 v216, 6, v212
	global_load_dwordx4 v[32:35], v172, s[38:39] offset:2048
	global_load_dwordx4 v[36:39], v172, s[38:39] offset:2560
	s_mov_b64 exec, s[62:63]
	global_load_dwordx4 v[148:151], v216, s[42:43] offset:0
	global_load_dwordx4 v[152:155], v216, s[42:43] offset:16
	global_load_dwordx4 v[156:159], v216, s[42:43] offset:32
	global_load_dwordx4 v[160:163], v216, s[42:43] offset:48
	s_mov_b64 exec, -1
	v_add_u32_e32 v212, 192, v217
	v_max_i32_e32 v212, 0, v212
	v_min_u32_e32 v212, 0x1fff, v212
	v_mul_lo_u32 v172, v212, s60
	v_add_u32_e32 v172, v172, v4
	v_lshlrev_b32_e32 v216, 6, v212
	global_load_dwordx4 v[40:43], v172, s[38:39] offset:2048
	global_load_dwordx4 v[44:47], v172, s[38:39] offset:2560
	s_mov_b64 exec, s[62:63]
	global_load_dwordx4 v[164:167], v216, s[42:43] offset:0
	global_load_dwordx4 v[168:171], v216, s[42:43] offset:16
	global_load_dwordx4 v[176:179], v216, s[42:43] offset:32
	global_load_dwordx4 v[180:183], v216, s[42:43] offset:48
	s_mov_b64 exec, -1
	v_add_u32_e32 v212, 256, v217
	v_max_i32_e32 v212, 0, v212
	v_min_u32_e32 v212, 0x1fff, v212
	v_mul_lo_u32 v172, v212, s60
	v_add_u32_e32 v172, v172, v4
	v_lshlrev_b32_e32 v216, 6, v212
	global_load_dwordx4 v[48:51], v172, s[38:39] offset:2048
	global_load_dwordx4 v[52:55], v172, s[38:39] offset:2560
	s_mov_b64 exec, s[62:63]
	global_load_dwordx4 v[184:187], v216, s[42:43] offset:0
	global_load_dwordx4 v[188:191], v216, s[42:43] offset:16
	global_load_dwordx4 v[192:195], v216, s[42:43] offset:32
	global_load_dwordx4 v[196:199], v216, s[42:43] offset:48
	s_mov_b64 exec, -1
	v_add_u32_e32 v212, 320, v217
	v_max_i32_e32 v212, 0, v212
	v_min_u32_e32 v212, 0x1fff, v212
	v_mul_lo_u32 v172, v212, s60
	v_add_u32_e32 v172, v172, v4
	v_lshlrev_b32_e32 v216, 6, v212
	global_load_dwordx4 v[56:59], v172, s[38:39] offset:2048
	global_load_dwordx4 v[60:63], v172, s[38:39] offset:2560
	s_mov_b64 exec, s[62:63]
	global_load_dwordx4 v[200:203], v216, s[42:43] offset:0
	global_load_dwordx4 v[204:207], v216, s[42:43] offset:16
	global_load_dwordx4 v[208:211], v216, s[42:43] offset:32
	global_load_dwordx4 v[234:237], v216, s[42:43] offset:48
	s_mov_b64 exec, -1
	s_cmp_eq_u32 s53, 0
	s_cbranch_scc1 .Lat_skip0_1
	s_waitcnt vmcnt(30)
	v_lshlrev_b32_e32 v72, 16, v16
	v_and_b32_e32 v73, 0xffff0000, v16
	v_lshlrev_b32_e32 v74, 16, v17
	v_and_b32_e32 v75, 0xffff0000, v17
	v_lshlrev_b32_e32 v76, 16, v18
	v_and_b32_e32 v77, 0xffff0000, v18
	v_lshlrev_b32_e32 v78, 16, v19
	v_and_b32_e32 v79, 0xffff0000, v19
	v_mul_f32_e32 v88, v72, v72
	v_fmac_f32_e32 v88, v73, v73
	v_fmac_f32_e32 v88, v74, v74
	v_fmac_f32_e32 v88, v75, v75
	v_fmac_f32_e32 v88, v76, v76
	v_fmac_f32_e32 v88, v77, v77
	v_fmac_f32_e32 v88, v78, v78
	v_fmac_f32_e32 v88, v79, v79
	s_nop 1
	v_add_f32_dpp v88, v88, v88 quad_perm:[1,0,3,2] row_mask:0xf bank_mask:0xf
	s_nop 1
	v_add_f32_dpp v88, v88, v88 quad_perm:[2,3,0,1] row_mask:0xf bank_mask:0xf
	s_nop 1
	v_add_f32_dpp v88, v88, v88 row_half_mirror row_mask:0xf bank_mask:0xf
	s_nop 1
	v_fmamk_f32 v88, v88, 0x3c800000, v174
	v_rsq_f32_e32 v89, v88
	s_nop 0
	v_mul_f32_e32 v72, v72, v89
	v_mul_f32_e32 v73, v73, v89
	v_mul_f32_e32 v74, v74, v89
	v_mul_f32_e32 v75, v75, v89
	v_mul_f32_e32 v76, v76, v89
	v_mul_f32_e32 v77, v77, v89
	v_mul_f32_e32 v78, v78, v89
	v_mul_f32_e32 v79, v79, v89
	v_mul_f32_e32 v72, v72, v64
	v_mul_f32_e32 v73, v73, v65
	v_mul_f32_e32 v74, v74, v66
	v_mul_f32_e32 v75, v75, v67
	v_mul_f32_e32 v76, v76, v68
	v_mul_f32_e32 v77, v77, v69
	v_mul_f32_e32 v78, v78, v70
	v_mul_f32_e32 v79, v79, v71
	s_mov_b64 exec, s[62:63]
	s_nop 4
	v_mov_b32_dpp v80, v72 quad_perm:[1,0,3,2] row_mask:0xf bank_mask:0xf
	v_mov_b32_dpp v81, v73 quad_perm:[1,0,3,2] row_mask:0xf bank_mask:0xf
	v_mov_b32_dpp v82, v74 quad_perm:[1,0,3,2] row_mask:0xf bank_mask:0xf
	v_mov_b32_dpp v83, v75 quad_perm:[1,0,3,2] row_mask:0xf bank_mask:0xf
	v_mov_b32_dpp v84, v76 quad_perm:[1,0,3,2] row_mask:0xf bank_mask:0xf
	v_mov_b32_dpp v85, v77 quad_perm:[1,0,3,2] row_mask:0xf bank_mask:0xf
	v_mov_b32_dpp v86, v78 quad_perm:[1,0,3,2] row_mask:0xf bank_mask:0xf
	v_mov_b32_dpp v87, v79 quad_perm:[1,0,3,2] row_mask:0xf bank_mask:0xf
	s_nop 0
	v_mul_f32_e32 v80, v80, v117
	v_mul_f32_e32 v81, v81, v119
	v_mul_f32_e32 v82, v82, v121
	v_mul_f32_e32 v83, v83, v123
	v_mul_f32_e32 v84, v84, v125
	v_mul_f32_e32 v85, v85, v127
	v_mul_f32_e32 v86, v86, v129
	v_mul_f32_e32 v87, v87, v131
	v_cndmask_b32_e64 v80, v80, -v80, s[64:65]
	v_cndmask_b32_e64 v81, v81, -v81, s[64:65]
	v_cndmask_b32_e64 v82, v82, -v82, s[64:65]
	v_cndmask_b32_e64 v83, v83, -v83, s[64:65]
	v_cndmask_b32_e64 v84, v84, -v84, s[64:65]
	v_cndmask_b32_e64 v85, v85, -v85, s[64:65]
	v_cndmask_b32_e64 v86, v86, -v86, s[64:65]
	v_cndmask_b32_e64 v87, v87, -v87, s[64:65]
	v_fma_f32 v72, v72, v116, v80
	v_fma_f32 v73, v73, v118, v81
	v_fma_f32 v74, v74, v120, v82
	v_fma_f32 v75, v75, v122, v83
	v_fma_f32 v76, v76, v124, v84
	v_fma_f32 v77, v77, v126, v85
	v_fma_f32 v78, v78, v128, v86
	v_fma_f32 v79, v79, v130, v87
	s_mov_b64 exec, -1
	v_cvt_pk_bf16_f32 v92, v72, v73
	v_cvt_pk_bf16_f32 v93, v74, v75
	v_cvt_pk_bf16_f32 v94, v76, v77
	v_cvt_pk_bf16_f32 v95, v78, v79
	ds_write_b128 v5, v[92:95] offset:0
	ds_write_b128 v6, v[20:23] offset:0
.Lat_skip0_1:
	s_cmp_eq_u32 s53, 0
	s_cbranch_scc1 .Lat_skip1_2
	s_waitcnt vmcnt(24)
	v_lshlrev_b32_e32 v72, 16, v24
	v_and_b32_e32 v73, 0xffff0000, v24
	v_lshlrev_b32_e32 v74, 16, v25
	v_and_b32_e32 v75, 0xffff0000, v25
	v_lshlrev_b32_e32 v76, 16, v26
	v_and_b32_e32 v77, 0xffff0000, v26
	v_lshlrev_b32_e32 v78, 16, v27
	v_and_b32_e32 v79, 0xffff0000, v27
	v_mul_f32_e32 v88, v72, v72
	v_fmac_f32_e32 v88, v73, v73
	v_fmac_f32_e32 v88, v74, v74
	v_fmac_f32_e32 v88, v75, v75
	v_fmac_f32_e32 v88, v76, v76
	v_fmac_f32_e32 v88, v77, v77
	v_fmac_f32_e32 v88, v78, v78
	v_fmac_f32_e32 v88, v79, v79
	s_nop 1
	v_add_f32_dpp v88, v88, v88 quad_perm:[1,0,3,2] row_mask:0xf bank_mask:0xf
	s_nop 1
	v_add_f32_dpp v88, v88, v88 quad_perm:[2,3,0,1] row_mask:0xf bank_mask:0xf
	s_nop 1
	v_add_f32_dpp v88, v88, v88 row_half_mirror row_mask:0xf bank_mask:0xf
	s_nop 1
	v_fmamk_f32 v88, v88, 0x3c800000, v174
	v_rsq_f32_e32 v89, v88
	s_nop 0
	v_mul_f32_e32 v72, v72, v89
	v_mul_f32_e32 v73, v73, v89
	v_mul_f32_e32 v74, v74, v89
	v_mul_f32_e32 v75, v75, v89
	v_mul_f32_e32 v76, v76, v89
	v_mul_f32_e32 v77, v77, v89
	v_mul_f32_e32 v78, v78, v89
	v_mul_f32_e32 v79, v79, v89
	v_mul_f32_e32 v72, v72, v64
	v_mul_f32_e32 v73, v73, v65
	v_mul_f32_e32 v74, v74, v66
	v_mul_f32_e32 v75, v75, v67
	v_mul_f32_e32 v76, v76, v68
	v_mul_f32_e32 v77, v77, v69
	v_mul_f32_e32 v78, v78, v70
	v_mul_f32_e32 v79, v79, v71
	s_mov_b64 exec, s[62:63]
	s_nop 4
	v_mov_b32_dpp v80, v72 quad_perm:[1,0,3,2] row_mask:0xf bank_mask:0xf
	v_mov_b32_dpp v81, v73 quad_perm:[1,0,3,2] row_mask:0xf bank_mask:0xf
	v_mov_b32_dpp v82, v74 quad_perm:[1,0,3,2] row_mask:0xf bank_mask:0xf
	v_mov_b32_dpp v83, v75 quad_perm:[1,0,3,2] row_mask:0xf bank_mask:0xf
	v_mov_b32_dpp v84, v76 quad_perm:[1,0,3,2] row_mask:0xf bank_mask:0xf
	v_mov_b32_dpp v85, v77 quad_perm:[1,0,3,2] row_mask:0xf bank_mask:0xf
	v_mov_b32_dpp v86, v78 quad_perm:[1,0,3,2] row_mask:0xf bank_mask:0xf
	v_mov_b32_dpp v87, v79 quad_perm:[1,0,3,2] row_mask:0xf bank_mask:0xf
	s_nop 0
	v_mul_f32_e32 v80, v80, v133
	v_mul_f32_e32 v81, v81, v135
	v_mul_f32_e32 v82, v82, v137
	v_mul_f32_e32 v83, v83, v139
	v_mul_f32_e32 v84, v84, v141
	v_mul_f32_e32 v85, v85, v143
	v_mul_f32_e32 v86, v86, v145
	v_mul_f32_e32 v87, v87, v147
	v_cndmask_b32_e64 v80, v80, -v80, s[64:65]
	v_cndmask_b32_e64 v81, v81, -v81, s[64:65]
	v_cndmask_b32_e64 v82, v82, -v82, s[64:65]
	v_cndmask_b32_e64 v83, v83, -v83, s[64:65]
	v_cndmask_b32_e64 v84, v84, -v84, s[64:65]
	v_cndmask_b32_e64 v85, v85, -v85, s[64:65]
	v_cndmask_b32_e64 v86, v86, -v86, s[64:65]
	v_cndmask_b32_e64 v87, v87, -v87, s[64:65]
	v_fma_f32 v72, v72, v132, v80
	v_fma_f32 v73, v73, v134, v81
	v_fma_f32 v74, v74, v136, v82
	v_fma_f32 v75, v75, v138, v83
	v_fma_f32 v76, v76, v140, v84
	v_fma_f32 v77, v77, v142, v85
	v_fma_f32 v78, v78, v144, v86
	v_fma_f32 v79, v79, v146, v87
	s_mov_b64 exec, -1
	v_cvt_pk_bf16_f32 v92, v72, v73
	v_cvt_pk_bf16_f32 v93, v74, v75
	v_cvt_pk_bf16_f32 v94, v76, v77
	v_cvt_pk_bf16_f32 v95, v78, v79
	ds_write_b128 v5, v[92:95] offset:9216
	ds_write_b128 v6, v[28:31] offset:9216
.Lat_skip1_2:
	global_load_dwordx4 v[116:119], v12, s[72:73] offset:0
	global_load_dwordx4 v[120:123], v12, s[72:73] offset:16
	global_load_dwordx4 v[124:127], v12, s[72:73] offset:32
	global_load_dwordx4 v[128:131], v12, s[72:73] offset:48
	global_load_dwordx4 v[132:135], v12, s[72:73] offset:2048
	global_load_dwordx4 v[136:139], v12, s[72:73] offset:2064
	global_load_dwordx4 v[140:143], v12, s[72:73] offset:2080
	global_load_dwordx4 v[144:147], v12, s[72:73] offset:2096
	s_waitcnt vmcnt(26)
	v_lshlrev_b32_e32 v72, 16, v32
	v_and_b32_e32 v73, 0xffff0000, v32
	v_lshlrev_b32_e32 v74, 16, v33
	v_and_b32_e32 v75, 0xffff0000, v33
	v_lshlrev_b32_e32 v76, 16, v34
	v_and_b32_e32 v77, 0xffff0000, v34
	v_lshlrev_b32_e32 v78, 16, v35
	v_and_b32_e32 v79, 0xffff0000, v35
	v_mul_f32_e32 v88, v72, v72
	v_fmac_f32_e32 v88, v73, v73
	v_fmac_f32_e32 v88, v74, v74
	v_fmac_f32_e32 v88, v75, v75
	v_fmac_f32_e32 v88, v76, v76
	v_fmac_f32_e32 v88, v77, v77
	v_fmac_f32_e32 v88, v78, v78
	v_fmac_f32_e32 v88, v79, v79
	s_nop 1
	v_add_f32_dpp v88, v88, v88 quad_perm:[1,0,3,2] row_mask:0xf bank_mask:0xf
	s_nop 1
	v_add_f32_dpp v88, v88, v88 quad_perm:[2,3,0,1] row_mask:0xf bank_mask:0xf
	s_nop 1
	v_add_f32_dpp v88, v88, v88 row_half_mirror row_mask:0xf bank_mask:0xf
	s_nop 1
	v_fmamk_f32 v88, v88, 0x3c800000, v174
	v_rsq_f32_e32 v89, v88
	s_nop 0
	v_mul_f32_e32 v72, v72, v89
	v_mul_f32_e32 v73, v73, v89
	v_mul_f32_e32 v74, v74, v89
	v_mul_f32_e32 v75, v75, v89
	v_mul_f32_e32 v76, v76, v89
	v_mul_f32_e32 v77, v77, v89
	v_mul_f32_e32 v78, v78, v89
	v_mul_f32_e32 v79, v79, v89
	v_mul_f32_e32 v72, v72, v64
	v_mul_f32_e32 v73, v73, v65
	v_mul_f32_e32 v74, v74, v66
	v_mul_f32_e32 v75, v75, v67
	v_mul_f32_e32 v76, v76, v68
	v_mul_f32_e32 v77, v77, v69
	v_mul_f32_e32 v78, v78, v70
	v_mul_f32_e32 v79, v79, v71
	s_mov_b64 exec, s[62:63]
	s_nop 4
	v_mov_b32_dpp v80, v72 quad_perm:[1,0,3,2] row_mask:0xf bank_mask:0xf
	v_mov_b32_dpp v81, v73 quad_perm:[1,0,3,2] row_mask:0xf bank_mask:0xf
	v_mov_b32_dpp v82, v74 quad_perm:[1,0,3,2] row_mask:0xf bank_mask:0xf
	v_mov_b32_dpp v83, v75 quad_perm:[1,0,3,2] row_mask:0xf bank_mask:0xf
	v_mov_b32_dpp v84, v76 quad_perm:[1,0,3,2] row_mask:0xf bank_mask:0xf
	v_mov_b32_dpp v85, v77 quad_perm:[1,0,3,2] row_mask:0xf bank_mask:0xf
	v_mov_b32_dpp v86, v78 quad_perm:[1,0,3,2] row_mask:0xf bank_mask:0xf
	v_mov_b32_dpp v87, v79 quad_perm:[1,0,3,2] row_mask:0xf bank_mask:0xf
	s_nop 0
	v_mul_f32_e32 v80, v80, v149
	v_mul_f32_e32 v81, v81, v151
	v_mul_f32_e32 v82, v82, v153
	v_mul_f32_e32 v83, v83, v155
	v_mul_f32_e32 v84, v84, v157
	v_mul_f32_e32 v85, v85, v159
	v_mul_f32_e32 v86, v86, v161
	v_mul_f32_e32 v87, v87, v163
	v_cndmask_b32_e64 v80, v80, -v80, s[64:65]
	v_cndmask_b32_e64 v81, v81, -v81, s[64:65]
	v_cndmask_b32_e64 v82, v82, -v82, s[64:65]
	v_cndmask_b32_e64 v83, v83, -v83, s[64:65]
	v_cndmask_b32_e64 v84, v84, -v84, s[64:65]
	v_cndmask_b32_e64 v85, v85, -v85, s[64:65]
	v_cndmask_b32_e64 v86, v86, -v86, s[64:65]
	v_cndmask_b32_e64 v87, v87, -v87, s[64:65]
	v_fma_f32 v72, v72, v148, v80
	v_fma_f32 v73, v73, v150, v81
	v_fma_f32 v74, v74, v152, v82
	v_fma_f32 v75, v75, v154, v83
	v_fma_f32 v76, v76, v156, v84
	v_fma_f32 v77, v77, v158, v85
	v_fma_f32 v78, v78, v160, v86
	v_fma_f32 v79, v79, v162, v87
	s_mov_b64 exec, -1
	v_cvt_pk_bf16_f32 v92, v72, v73
	v_cvt_pk_bf16_f32 v93, v74, v75
	v_cvt_pk_bf16_f32 v94, v76, v77
	v_cvt_pk_bf16_f32 v95, v78, v79
	ds_write_b128 v5, v[92:95] offset:18432
	ds_write_b128 v6, v[36:39] offset:18432
.Lat_skip2_3:
	s_waitcnt vmcnt(20)
	v_lshlrev_b32_e32 v72, 16, v40
	v_and_b32_e32 v73, 0xffff0000, v40
	v_lshlrev_b32_e32 v74, 16, v41
	v_and_b32_e32 v75, 0xffff0000, v41
	v_lshlrev_b32_e32 v76, 16, v42
	v_and_b32_e32 v77, 0xffff0000, v42
	v_lshlrev_b32_e32 v78, 16, v43
	v_and_b32_e32 v79, 0xffff0000, v43
	v_mul_f32_e32 v88, v72, v72
	v_fmac_f32_e32 v88, v73, v73
	v_fmac_f32_e32 v88, v74, v74
	v_fmac_f32_e32 v88, v75, v75
	v_fmac_f32_e32 v88, v76, v76
	v_fmac_f32_e32 v88, v77, v77
	v_fmac_f32_e32 v88, v78, v78
	v_fmac_f32_e32 v88, v79, v79
	s_nop 1
	v_add_f32_dpp v88, v88, v88 quad_perm:[1,0,3,2] row_mask:0xf bank_mask:0xf
	s_nop 1
	v_add_f32_dpp v88, v88, v88 quad_perm:[2,3,0,1] row_mask:0xf bank_mask:0xf
	s_nop 1
	v_add_f32_dpp v88, v88, v88 row_half_mirror row_mask:0xf bank_mask:0xf
	s_nop 1
	v_fmamk_f32 v88, v88, 0x3c800000, v174
	v_rsq_f32_e32 v89, v88
	s_nop 0
	v_mul_f32_e32 v72, v72, v89
	v_mul_f32_e32 v73, v73, v89
	v_mul_f32_e32 v74, v74, v89
	v_mul_f32_e32 v75, v75, v89
	v_mul_f32_e32 v76, v76, v89
	v_mul_f32_e32 v77, v77, v89
	v_mul_f32_e32 v78, v78, v89
	v_mul_f32_e32 v79, v79, v89
	v_mul_f32_e32 v72, v72, v64
	v_mul_f32_e32 v73, v73, v65
	v_mul_f32_e32 v74, v74, v66
	v_mul_f32_e32 v75, v75, v67
	v_mul_f32_e32 v76, v76, v68
	v_mul_f32_e32 v77, v77, v69
	v_mul_f32_e32 v78, v78, v70
	v_mul_f32_e32 v79, v79, v71
	s_mov_b64 exec, s[62:63]
	s_nop 4
	v_mov_b32_dpp v80, v72 quad_perm:[1,0,3,2] row_mask:0xf bank_mask:0xf
	v_mov_b32_dpp v81, v73 quad_perm:[1,0,3,2] row_mask:0xf bank_mask:0xf
	v_mov_b32_dpp v82, v74 quad_perm:[1,0,3,2] row_mask:0xf bank_mask:0xf
	v_mov_b32_dpp v83, v75 quad_perm:[1,0,3,2] row_mask:0xf bank_mask:0xf
	v_mov_b32_dpp v84, v76 quad_perm:[1,0,3,2] row_mask:0xf bank_mask:0xf
	v_mov_b32_dpp v85, v77 quad_perm:[1,0,3,2] row_mask:0xf bank_mask:0xf
	v_mov_b32_dpp v86, v78 quad_perm:[1,0,3,2] row_mask:0xf bank_mask:0xf
	v_mov_b32_dpp v87, v79 quad_perm:[1,0,3,2] row_mask:0xf bank_mask:0xf
	s_nop 0
	v_mul_f32_e32 v80, v80, v165
	v_mul_f32_e32 v81, v81, v167
	v_mul_f32_e32 v82, v82, v169
	v_mul_f32_e32 v83, v83, v171
	v_mul_f32_e32 v84, v84, v177
	v_mul_f32_e32 v85, v85, v179
	v_mul_f32_e32 v86, v86, v181
	v_mul_f32_e32 v87, v87, v183
	v_cndmask_b32_e64 v80, v80, -v80, s[64:65]
	v_cndmask_b32_e64 v81, v81, -v81, s[64:65]
	v_cndmask_b32_e64 v82, v82, -v82, s[64:65]
	v_cndmask_b32_e64 v83, v83, -v83, s[64:65]
	v_cndmask_b32_e64 v84, v84, -v84, s[64:65]
	v_cndmask_b32_e64 v85, v85, -v85, s[64:65]
	v_cndmask_b32_e64 v86, v86, -v86, s[64:65]
	v_cndmask_b32_e64 v87, v87, -v87, s[64:65]
	v_fma_f32 v72, v72, v164, v80
	v_fma_f32 v73, v73, v166, v81
	v_fma_f32 v74, v74, v168, v82
	v_fma_f32 v75, v75, v170, v83
	v_fma_f32 v76, v76, v176, v84
	v_fma_f32 v77, v77, v178, v85
	v_fma_f32 v78, v78, v180, v86
	v_fma_f32 v79, v79, v182, v87
	s_mov_b64 exec, -1
	v_cvt_pk_bf16_f32 v92, v72, v73
	v_cvt_pk_bf16_f32 v93, v74, v75
	v_cvt_pk_bf16_f32 v94, v76, v77
	v_cvt_pk_bf16_f32 v95, v78, v79
	ds_write_b128 v5, v[92:95] offset:27648
	ds_write_b128 v6, v[44:47] offset:27648
.Lat_skip3_4:
	v_lshlrev_b32_e32 v212, 5, v2
	global_load_dwordx4 v[148:151], v212, s[48:49] offset:0
	global_load_dwordx4 v[152:155], v212, s[48:49] offset:16
	global_load_dwordx4 v[156:159], v212, s[48:49] offset:64
	global_load_dwordx4 v[160:163], v212, s[48:49] offset:80
	global_load_dwordx4 v[164:167], v212, s[48:49] offset:128
	global_load_dwordx4 v[168:171], v212, s[48:49] offset:144
	global_load_dwordx4 v[176:179], v212, s[48:49] offset:192
	global_load_dwordx4 v[180:183], v212, s[48:49] offset:208
	s_cmp_eq_u32 s53, 63
	s_cbranch_scc1 .Lat_skip4_5
	s_waitcnt vmcnt(22)
	v_lshlrev_b32_e32 v72, 16, v48
	v_and_b32_e32 v73, 0xffff0000, v48
	v_lshlrev_b32_e32 v74, 16, v49
	v_and_b32_e32 v75, 0xffff0000, v49
	v_lshlrev_b32_e32 v76, 16, v50
	v_and_b32_e32 v77, 0xffff0000, v50
	v_lshlrev_b32_e32 v78, 16, v51
	v_and_b32_e32 v79, 0xffff0000, v51
	v_mul_f32_e32 v88, v72, v72
	v_fmac_f32_e32 v88, v73, v73
	v_fmac_f32_e32 v88, v74, v74
	v_fmac_f32_e32 v88, v75, v75
	v_fmac_f32_e32 v88, v76, v76
	v_fmac_f32_e32 v88, v77, v77
	v_fmac_f32_e32 v88, v78, v78
	v_fmac_f32_e32 v88, v79, v79
	s_nop 1
	v_add_f32_dpp v88, v88, v88 quad_perm:[1,0,3,2] row_mask:0xf bank_mask:0xf
	s_nop 1
	v_add_f32_dpp v88, v88, v88 quad_perm:[2,3,0,1] row_mask:0xf bank_mask:0xf
	s_nop 1
	v_add_f32_dpp v88, v88, v88 row_half_mirror row_mask:0xf bank_mask:0xf
	s_nop 1
	v_fmamk_f32 v88, v88, 0x3c800000, v174
	v_rsq_f32_e32 v89, v88
	s_nop 0
	v_mul_f32_e32 v72, v72, v89
	v_mul_f32_e32 v73, v73, v89
	v_mul_f32_e32 v74, v74, v89
	v_mul_f32_e32 v75, v75, v89
	v_mul_f32_e32 v76, v76, v89
	v_mul_f32_e32 v77, v77, v89
	v_mul_f32_e32 v78, v78, v89
	v_mul_f32_e32 v79, v79, v89
	v_mul_f32_e32 v72, v72, v64
	v_mul_f32_e32 v73, v73, v65
	v_mul_f32_e32 v74, v74, v66
	v_mul_f32_e32 v75, v75, v67
	v_mul_f32_e32 v76, v76, v68
	v_mul_f32_e32 v77, v77, v69
	v_mul_f32_e32 v78, v78, v70
	v_mul_f32_e32 v79, v79, v71
	s_mov_b64 exec, s[62:63]
	s_nop 4
	v_mov_b32_dpp v80, v72 quad_perm:[1,0,3,2] row_mask:0xf bank_mask:0xf
	v_mov_b32_dpp v81, v73 quad_perm:[1,0,3,2] row_mask:0xf bank_mask:0xf
	v_mov_b32_dpp v82, v74 quad_perm:[1,0,3,2] row_mask:0xf bank_mask:0xf
	v_mov_b32_dpp v83, v75 quad_perm:[1,0,3,2] row_mask:0xf bank_mask:0xf
	v_mov_b32_dpp v84, v76 quad_perm:[1,0,3,2] row_mask:0xf bank_mask:0xf
	v_mov_b32_dpp v85, v77 quad_perm:[1,0,3,2] row_mask:0xf bank_mask:0xf
	v_mov_b32_dpp v86, v78 quad_perm:[1,0,3,2] row_mask:0xf bank_mask:0xf
	v_mov_b32_dpp v87, v79 quad_perm:[1,0,3,2] row_mask:0xf bank_mask:0xf
	s_nop 0
	v_mul_f32_e32 v80, v80, v185
	v_mul_f32_e32 v81, v81, v187
	v_mul_f32_e32 v82, v82, v189
	v_mul_f32_e32 v83, v83, v191
	v_mul_f32_e32 v84, v84, v193
	v_mul_f32_e32 v85, v85, v195
	v_mul_f32_e32 v86, v86, v197
	v_mul_f32_e32 v87, v87, v199
	v_cndmask_b32_e64 v80, v80, -v80, s[64:65]
	v_cndmask_b32_e64 v81, v81, -v81, s[64:65]
	v_cndmask_b32_e64 v82, v82, -v82, s[64:65]
	v_cndmask_b32_e64 v83, v83, -v83, s[64:65]
	v_cndmask_b32_e64 v84, v84, -v84, s[64:65]
	v_cndmask_b32_e64 v85, v85, -v85, s[64:65]
	v_cndmask_b32_e64 v86, v86, -v86, s[64:65]
	v_cndmask_b32_e64 v87, v87, -v87, s[64:65]
	v_fma_f32 v72, v72, v184, v80
	v_fma_f32 v73, v73, v186, v81
	v_fma_f32 v74, v74, v188, v82
	v_fma_f32 v75, v75, v190, v83
	v_fma_f32 v76, v76, v192, v84
	v_fma_f32 v77, v77, v194, v85
	v_fma_f32 v78, v78, v196, v86
	v_fma_f32 v79, v79, v198, v87
	s_mov_b64 exec, -1
	v_cvt_pk_bf16_f32 v92, v72, v73
	v_cvt_pk_bf16_f32 v93, v74, v75
	v_cvt_pk_bf16_f32 v94, v76, v77
	v_cvt_pk_bf16_f32 v95, v78, v79
	ds_write_b128 v5, v[92:95] offset:36864
	ds_write_b128 v6, v[52:55] offset:36864
.Lat_skip4_5:
	s_cmp_eq_u32 s53, 63
	s_cbranch_scc1 .Lat_skip5_6
	s_waitcnt vmcnt(16)
	v_lshlrev_b32_e32 v72, 16, v56
	v_and_b32_e32 v73, 0xffff0000, v56
	v_lshlrev_b32_e32 v74, 16, v57
	v_and_b32_e32 v75, 0xffff0000, v57
	v_lshlrev_b32_e32 v76, 16, v58
	v_and_b32_e32 v77, 0xffff0000, v58
	v_lshlrev_b32_e32 v78, 16, v59
	v_and_b32_e32 v79, 0xffff0000, v59
	v_mul_f32_e32 v88, v72, v72
	v_fmac_f32_e32 v88, v73, v73
	v_fmac_f32_e32 v88, v74, v74
	v_fmac_f32_e32 v88, v75, v75
	v_fmac_f32_e32 v88, v76, v76
	v_fmac_f32_e32 v88, v77, v77
	v_fmac_f32_e32 v88, v78, v78
	v_fmac_f32_e32 v88, v79, v79
	s_nop 1
	v_add_f32_dpp v88, v88, v88 quad_perm:[1,0,3,2] row_mask:0xf bank_mask:0xf
	s_nop 1
	v_add_f32_dpp v88, v88, v88 quad_perm:[2,3,0,1] row_mask:0xf bank_mask:0xf
	s_nop 1
	v_add_f32_dpp v88, v88, v88 row_half_mirror row_mask:0xf bank_mask:0xf
	s_nop 1
	v_fmamk_f32 v88, v88, 0x3c800000, v174
	v_rsq_f32_e32 v89, v88
	s_nop 0
	v_mul_f32_e32 v72, v72, v89
	v_mul_f32_e32 v73, v73, v89
	v_mul_f32_e32 v74, v74, v89
	v_mul_f32_e32 v75, v75, v89
	v_mul_f32_e32 v76, v76, v89
	v_mul_f32_e32 v77, v77, v89
	v_mul_f32_e32 v78, v78, v89
	v_mul_f32_e32 v79, v79, v89
	v_mul_f32_e32 v72, v72, v64
	v_mul_f32_e32 v73, v73, v65
	v_mul_f32_e32 v74, v74, v66
	v_mul_f32_e32 v75, v75, v67
	v_mul_f32_e32 v76, v76, v68
	v_mul_f32_e32 v77, v77, v69
	v_mul_f32_e32 v78, v78, v70
	v_mul_f32_e32 v79, v79, v71
	s_mov_b64 exec, s[62:63]
	s_nop 4
	v_mov_b32_dpp v80, v72 quad_perm:[1,0,3,2] row_mask:0xf bank_mask:0xf
	v_mov_b32_dpp v81, v73 quad_perm:[1,0,3,2] row_mask:0xf bank_mask:0xf
	v_mov_b32_dpp v82, v74 quad_perm:[1,0,3,2] row_mask:0xf bank_mask:0xf
	v_mov_b32_dpp v83, v75 quad_perm:[1,0,3,2] row_mask:0xf bank_mask:0xf
	v_mov_b32_dpp v84, v76 quad_perm:[1,0,3,2] row_mask:0xf bank_mask:0xf
	v_mov_b32_dpp v85, v77 quad_perm:[1,0,3,2] row_mask:0xf bank_mask:0xf
	v_mov_b32_dpp v86, v78 quad_perm:[1,0,3,2] row_mask:0xf bank_mask:0xf
	v_mov_b32_dpp v87, v79 quad_perm:[1,0,3,2] row_mask:0xf bank_mask:0xf
	s_nop 0
	v_mul_f32_e32 v80, v80, v201
	v_mul_f32_e32 v81, v81, v203
	v_mul_f32_e32 v82, v82, v205
	v_mul_f32_e32 v83, v83, v207
	v_mul_f32_e32 v84, v84, v209
	v_mul_f32_e32 v85, v85, v211
	v_mul_f32_e32 v86, v86, v235
	v_mul_f32_e32 v87, v87, v237
	v_cndmask_b32_e64 v80, v80, -v80, s[64:65]
	v_cndmask_b32_e64 v81, v81, -v81, s[64:65]
	v_cndmask_b32_e64 v82, v82, -v82, s[64:65]
	v_cndmask_b32_e64 v83, v83, -v83, s[64:65]
	v_cndmask_b32_e64 v84, v84, -v84, s[64:65]
	v_cndmask_b32_e64 v85, v85, -v85, s[64:65]
	v_cndmask_b32_e64 v86, v86, -v86, s[64:65]
	v_cndmask_b32_e64 v87, v87, -v87, s[64:65]
	v_fma_f32 v72, v72, v200, v80
	v_fma_f32 v73, v73, v202, v81
	v_fma_f32 v74, v74, v204, v82
	v_fma_f32 v75, v75, v206, v83
	v_fma_f32 v76, v76, v208, v84
	v_fma_f32 v77, v77, v210, v85
	v_fma_f32 v78, v78, v234, v86
	v_fma_f32 v79, v79, v236, v87
	s_mov_b64 exec, -1
	v_cvt_pk_bf16_f32 v92, v72, v73
	v_cvt_pk_bf16_f32 v93, v74, v75
	v_cvt_pk_bf16_f32 v94, v76, v77
	v_cvt_pk_bf16_f32 v95, v78, v79
	ds_write_b128 v5, v[92:95] offset:46080
	ds_write_b128 v6, v[60:63] offset:46080
.Lat_skip5_6:
.Lat_stagedone:
	s_waitcnt vmcnt(0)
	s_waitcnt lgkmcnt(0)
	v_mov_b32_e32 v212, s11
	v_mul_f32_e32 v212, 0xbfb8aa3b, v212
	v_cndmask_b32_e64 v209, 1.0, 0, s[66:67]
	v_cndmask_b32_e64 v211, 1.0, 0, s[66:67]
	v_lshlrev_b32_e32 v16, 16, v96
	v_and_b32_e32 v17, 0xffff0000, v96
	v_lshlrev_b32_e32 v18, 16, v97
	v_and_b32_e32 v19, 0xffff0000, v97
	v_lshlrev_b32_e32 v20, 16, v98
	v_and_b32_e32 v21, 0xffff0000, v98
	v_lshlrev_b32_e32 v22, 16, v99
	v_and_b32_e32 v23, 0xffff0000, v99
	v_lshlrev_b32_e32 v24, 16, v100
	v_and_b32_e32 v25, 0xffff0000, v100
	v_lshlrev_b32_e32 v26, 16, v101
	v_and_b32_e32 v27, 0xffff0000, v101
	v_lshlrev_b32_e32 v28, 16, v102
	v_and_b32_e32 v29, 0xffff0000, v102
	v_lshlrev_b32_e32 v30, 16, v103
	v_and_b32_e32 v31, 0xffff0000, v103
	v_lshlrev_b32_e32 v32, 16, v104
	v_and_b32_e32 v33, 0xffff0000, v104
	v_lshlrev_b32_e32 v34, 16, v105
	v_and_b32_e32 v35, 0xffff0000, v105
	v_lshlrev_b32_e32 v36, 16, v106
	v_and_b32_e32 v37, 0xffff0000, v106
	v_lshlrev_b32_e32 v38, 16, v107
	v_and_b32_e32 v39, 0xffff0000, v107
	v_lshlrev_b32_e32 v40, 16, v108
	v_and_b32_e32 v41, 0xffff0000, v108
	v_lshlrev_b32_e32 v42, 16, v109
	v_and_b32_e32 v43, 0xffff0000, v109
	v_lshlrev_b32_e32 v44, 16, v110
	v_and_b32_e32 v45, 0xffff0000, v110
	v_lshlrev_b32_e32 v46, 16, v111
	v_and_b32_e32 v47, 0xffff0000, v111
	v_mul_f32_e32 v48, v16, v16
	v_fmac_f32_e32 v48, v17, v17
	v_fmac_f32_e32 v48, v18, v18
	v_fmac_f32_e32 v48, v19, v19
	v_fmac_f32_e32 v48, v20, v20
	v_fmac_f32_e32 v48, v21, v21
	v_fmac_f32_e32 v48, v22, v22
	v_fmac_f32_e32 v48, v23, v23
	v_fmac_f32_e32 v48, v24, v24
	v_fmac_f32_e32 v48, v25, v25
	v_fmac_f32_e32 v48, v26, v26
	v_fmac_f32_e32 v48, v27, v27
	v_fmac_f32_e32 v48, v28, v28
	v_fmac_f32_e32 v48, v29, v29
	v_fmac_f32_e32 v48, v30, v30
	v_fmac_f32_e32 v48, v31, v31
	v_fmac_f32_e32 v48, v32, v32
	v_fmac_f32_e32 v48, v33, v33
	v_fmac_f32_e32 v48, v34, v34
	v_fmac_f32_e32 v48, v35, v35
	v_fmac_f32_e32 v48, v36, v36
	v_fmac_f32_e32 v48, v37, v37
	v_fmac_f32_e32 v48, v38, v38
	v_fmac_f32_e32 v48, v39, v39
	v_fmac_f32_e32 v48, v40, v40
	v_fmac_f32_e32 v48, v41, v41
	v_fmac_f32_e32 v48, v42, v42
	v_fmac_f32_e32 v48, v43, v43
	v_fmac_f32_e32 v48, v44, v44
	v_fmac_f32_e32 v48, v45, v45
	v_fmac_f32_e32 v48, v46, v46
	v_fmac_f32_e32 v48, v47, v47
	v_mov_b32_e32 v49, v48
	s_nop 1
	v_permlane32_swap_b32_e32 v49, v48
	v_add_f32_e32 v48, v49, v48
	v_fmamk_f32 v48, v48, 0x3c800000, v174
	v_rsq_f32_e32 v48, v48
	v_mov_b32_e32 v50, 0x3e38aa3b
	v_pk_mul_f32 v[16:17], v[16:17], v[48:49] op_sel_hi:[1,0]
	v_pk_mul_f32 v[18:19], v[18:19], v[48:49] op_sel_hi:[1,0]
	v_pk_mul_f32 v[20:21], v[20:21], v[48:49] op_sel_hi:[1,0]
	v_pk_mul_f32 v[22:23], v[22:23], v[48:49] op_sel_hi:[1,0]
	v_pk_mul_f32 v[24:25], v[24:25], v[48:49] op_sel_hi:[1,0]
	v_pk_mul_f32 v[26:27], v[26:27], v[48:49] op_sel_hi:[1,0]
	v_pk_mul_f32 v[28:29], v[28:29], v[48:49] op_sel_hi:[1,0]
	v_pk_mul_f32 v[30:31], v[30:31], v[48:49] op_sel_hi:[1,0]
	v_pk_mul_f32 v[32:33], v[32:33], v[48:49] op_sel_hi:[1,0]
	v_pk_mul_f32 v[34:35], v[34:35], v[48:49] op_sel_hi:[1,0]
	v_pk_mul_f32 v[36:37], v[36:37], v[48:49] op_sel_hi:[1,0]
	v_pk_mul_f32 v[38:39], v[38:39], v[48:49] op_sel_hi:[1,0]
	v_pk_mul_f32 v[40:41], v[40:41], v[48:49] op_sel_hi:[1,0]
	v_pk_mul_f32 v[42:43], v[42:43], v[48:49] op_sel_hi:[1,0]
	v_pk_mul_f32 v[44:45], v[44:45], v[48:49] op_sel_hi:[1,0]
	v_pk_mul_f32 v[46:47], v[46:47], v[48:49] op_sel_hi:[1,0]
	v_pk_mul_f32 v[16:17], v[16:17], v[148:149]
	v_pk_mul_f32 v[18:19], v[18:19], v[150:151]
	v_pk_mul_f32 v[20:21], v[20:21], v[152:153]
	v_pk_mul_f32 v[22:23], v[22:23], v[154:155]
	v_pk_mul_f32 v[24:25], v[24:25], v[156:157]
	v_pk_mul_f32 v[26:27], v[26:27], v[158:159]
	v_pk_mul_f32 v[28:29], v[28:29], v[160:161]
	v_pk_mul_f32 v[30:31], v[30:31], v[162:163]
	v_pk_mul_f32 v[32:33], v[32:33], v[164:165]
	v_pk_mul_f32 v[34:35], v[34:35], v[166:167]
	v_pk_mul_f32 v[36:37], v[36:37], v[168:169]
	v_pk_mul_f32 v[38:39], v[38:39], v[170:171]
	v_pk_mul_f32 v[40:41], v[40:41], v[176:177]
	v_pk_mul_f32 v[42:43], v[42:43], v[178:179]
	v_pk_mul_f32 v[44:45], v[44:45], v[180:181]
	v_pk_mul_f32 v[46:47], v[46:47], v[182:183]
	v_mov_b32_e32 v60, v16
	v_mov_b32_e32 v61, v16
	s_nop 1
	v_permlane32_swap_b32_e32 v60, v61
	v_cndmask_b32_e64 v52, v61, v60, s[66:67]
	v_mov_b32_e32 v60, v17
	v_mov_b32_e32 v61, v17
	s_nop 1
	v_permlane32_swap_b32_e32 v60, v61
	v_cndmask_b32_e64 v53, v61, v60, s[66:67]
	v_mov_b32_e32 v60, v18
	v_mov_b32_e32 v61, v18
	s_nop 1
	v_permlane32_swap_b32_e32 v60, v61
	v_cndmask_b32_e64 v54, v61, v60, s[66:67]
	v_mov_b32_e32 v60, v19
	v_mov_b32_e32 v61, v19
	s_nop 1
	v_permlane32_swap_b32_e32 v60, v61
	v_cndmask_b32_e64 v55, v61, v60, s[66:67]
	v_mov_b32_e32 v60, v20
	v_mov_b32_e32 v61, v20
	s_nop 1
	v_permlane32_swap_b32_e32 v60, v61
	v_cndmask_b32_e64 v56, v61, v60, s[66:67]
	v_mov_b32_e32 v60, v21
	v_mov_b32_e32 v61, v21
	s_nop 1
	v_permlane32_swap_b32_e32 v60, v61
	v_cndmask_b32_e64 v57, v61, v60, s[66:67]
	v_mov_b32_e32 v60, v22
	v_mov_b32_e32 v61, v22
	s_nop 1
	v_permlane32_swap_b32_e32 v60, v61
	v_cndmask_b32_e64 v58, v61, v60, s[66:67]
	v_mov_b32_e32 v60, v23
	v_mov_b32_e32 v61, v23
	s_nop 1
	v_permlane32_swap_b32_e32 v60, v61
	v_cndmask_b32_e64 v59, v61, v60, s[66:67]
	v_mul_f32_e32 v52, v52, v117
	v_mul_f32_e32 v53, v53, v119
	v_mul_f32_e32 v54, v54, v121
	v_mul_f32_e32 v55, v55, v123
	v_mul_f32_e32 v56, v56, v125
	v_mul_f32_e32 v57, v57, v127
	v_mul_f32_e32 v58, v58, v129
	v_mul_f32_e32 v59, v59, v131
	v_cndmask_b32_e64 v52, -v52, v52, s[66:67]
	v_cndmask_b32_e64 v53, -v53, v53, s[66:67]
	v_cndmask_b32_e64 v54, -v54, v54, s[66:67]
	v_cndmask_b32_e64 v55, -v55, v55, s[66:67]
	v_cndmask_b32_e64 v56, -v56, v56, s[66:67]
	v_cndmask_b32_e64 v57, -v57, v57, s[66:67]
	v_cndmask_b32_e64 v58, -v58, v58, s[66:67]
	v_cndmask_b32_e64 v59, -v59, v59, s[66:67]
	v_fma_f32 v16, v16, v116, v52
	v_fma_f32 v17, v17, v118, v53
	v_fma_f32 v18, v18, v120, v54
	v_fma_f32 v19, v19, v122, v55
	v_fma_f32 v20, v20, v124, v56
	v_fma_f32 v21, v21, v126, v57
	v_fma_f32 v22, v22, v128, v58
	v_fma_f32 v23, v23, v130, v59
	v_pk_mul_f32 v[16:17], v[16:17], v[50:51] op_sel_hi:[1,0]
	v_pk_mul_f32 v[18:19], v[18:19], v[50:51] op_sel_hi:[1,0]
	v_pk_mul_f32 v[20:21], v[20:21], v[50:51] op_sel_hi:[1,0]
	v_pk_mul_f32 v[22:23], v[22:23], v[50:51] op_sel_hi:[1,0]
	v_pk_mul_f32 v[24:25], v[24:25], v[50:51] op_sel_hi:[1,0]
	v_pk_mul_f32 v[26:27], v[26:27], v[50:51] op_sel_hi:[1,0]
	v_pk_mul_f32 v[28:29], v[28:29], v[50:51] op_sel_hi:[1,0]
	v_pk_mul_f32 v[30:31], v[30:31], v[50:51] op_sel_hi:[1,0]
	v_pk_mul_f32 v[32:33], v[32:33], v[50:51] op_sel_hi:[1,0]
	v_pk_mul_f32 v[34:35], v[34:35], v[50:51] op_sel_hi:[1,0]
	v_pk_mul_f32 v[36:37], v[36:37], v[50:51] op_sel_hi:[1,0]
	v_pk_mul_f32 v[38:39], v[38:39], v[50:51] op_sel_hi:[1,0]
	v_pk_mul_f32 v[40:41], v[40:41], v[50:51] op_sel_hi:[1,0]
	v_pk_mul_f32 v[42:43], v[42:43], v[50:51] op_sel_hi:[1,0]
	v_pk_mul_f32 v[44:45], v[44:45], v[50:51] op_sel_hi:[1,0]
	v_pk_mul_f32 v[46:47], v[46:47], v[50:51] op_sel_hi:[1,0]
	v_cvt_pk_bf16_f32 v116, v16, v17
	v_cvt_pk_bf16_f32 v117, v18, v19
	v_cvt_pk_bf16_f32 v118, v20, v21
	v_cvt_pk_bf16_f32 v119, v22, v23
	v_cvt_pk_bf16_f32 v120, v24, v25
	v_cvt_pk_bf16_f32 v121, v26, v27
	v_cvt_pk_bf16_f32 v122, v28, v29
	v_cvt_pk_bf16_f32 v123, v30, v31
	v_cvt_pk_bf16_f32 v124, v32, v33
	v_cvt_pk_bf16_f32 v125, v34, v35
	v_cvt_pk_bf16_f32 v126, v36, v37
	v_cvt_pk_bf16_f32 v127, v38, v39
	v_cvt_pk_bf16_f32 v128, v40, v41
	v_cvt_pk_bf16_f32 v129, v42, v43
	v_cvt_pk_bf16_f32 v130, v44, v45
	v_cvt_pk_bf16_f32 v131, v46, v47
	v_lshlrev_b32_e32 v16, 16, v238
	v_and_b32_e32 v17, 0xffff0000, v238
	v_lshlrev_b32_e32 v18, 16, v239
	v_and_b32_e32 v19, 0xffff0000, v239
	v_lshlrev_b32_e32 v20, 16, v240
	v_and_b32_e32 v21, 0xffff0000, v240
	v_lshlrev_b32_e32 v22, 16, v241
	v_and_b32_e32 v23, 0xffff0000, v241
	v_lshlrev_b32_e32 v24, 16, v242
	v_and_b32_e32 v25, 0xffff0000, v242
	v_lshlrev_b32_e32 v26, 16, v243
	v_and_b32_e32 v27, 0xffff0000, v243
	v_lshlrev_b32_e32 v28, 16, v244
	v_and_b32_e32 v29, 0xffff0000, v244
	v_lshlrev_b32_e32 v30, 16, v245
	v_and_b32_e32 v31, 0xffff0000, v245
	v_lshlrev_b32_e32 v32, 16, v246
	v_and_b32_e32 v33, 0xffff0000, v246
	v_lshlrev_b32_e32 v34, 16, v247
	v_and_b32_e32 v35, 0xffff0000, v247
	v_lshlrev_b32_e32 v36, 16, v248
	v_and_b32_e32 v37, 0xffff0000, v248
	v_lshlrev_b32_e32 v38, 16, v249
	v_and_b32_e32 v39, 0xffff0000, v249
	v_lshlrev_b32_e32 v40, 16, v222
	v_and_b32_e32 v41, 0xffff0000, v222
	v_lshlrev_b32_e32 v42, 16, v223
	v_and_b32_e32 v43, 0xffff0000, v223
	v_lshlrev_b32_e32 v44, 16, v224
	v_and_b32_e32 v45, 0xffff0000, v224
	v_lshlrev_b32_e32 v46, 16, v225
	v_and_b32_e32 v47, 0xffff0000, v225
	v_mul_f32_e32 v48, v16, v16
	v_fmac_f32_e32 v48, v17, v17
	v_fmac_f32_e32 v48, v18, v18
	v_fmac_f32_e32 v48, v19, v19
	v_fmac_f32_e32 v48, v20, v20
	v_fmac_f32_e32 v48, v21, v21
	v_fmac_f32_e32 v48, v22, v22
	v_fmac_f32_e32 v48, v23, v23
	v_fmac_f32_e32 v48, v24, v24
	v_fmac_f32_e32 v48, v25, v25
	v_fmac_f32_e32 v48, v26, v26
	v_fmac_f32_e32 v48, v27, v27
	v_fmac_f32_e32 v48, v28, v28
	v_fmac_f32_e32 v48, v29, v29
	v_fmac_f32_e32 v48, v30, v30
	v_fmac_f32_e32 v48, v31, v31
	v_fmac_f32_e32 v48, v32, v32
	v_fmac_f32_e32 v48, v33, v33
	v_fmac_f32_e32 v48, v34, v34
	v_fmac_f32_e32 v48, v35, v35
	v_fmac_f32_e32 v48, v36, v36
	v_fmac_f32_e32 v48, v37, v37
	v_fmac_f32_e32 v48, v38, v38
	v_fmac_f32_e32 v48, v39, v39
	v_fmac_f32_e32 v48, v40, v40
	v_fmac_f32_e32 v48, v41, v41
	v_fmac_f32_e32 v48, v42, v42
	v_fmac_f32_e32 v48, v43, v43
	v_fmac_f32_e32 v48, v44, v44
	v_fmac_f32_e32 v48, v45, v45
	v_fmac_f32_e32 v48, v46, v46
	v_fmac_f32_e32 v48, v47, v47
	v_mov_b32_e32 v49, v48
	s_nop 1
	v_permlane32_swap_b32_e32 v49, v48
	v_add_f32_e32 v48, v49, v48
	v_fmamk_f32 v48, v48, 0x3c800000, v174
	v_rsq_f32_e32 v48, v48
	v_mov_b32_e32 v50, 0x3e38aa3b
	v_pk_mul_f32 v[16:17], v[16:17], v[48:49] op_sel_hi:[1,0]
	v_pk_mul_f32 v[18:19], v[18:19], v[48:49] op_sel_hi:[1,0]
	v_pk_mul_f32 v[20:21], v[20:21], v[48:49] op_sel_hi:[1,0]
	v_pk_mul_f32 v[22:23], v[22:23], v[48:49] op_sel_hi:[1,0]
	v_pk_mul_f32 v[24:25], v[24:25], v[48:49] op_sel_hi:[1,0]
	v_pk_mul_f32 v[26:27], v[26:27], v[48:49] op_sel_hi:[1,0]
	v_pk_mul_f32 v[28:29], v[28:29], v[48:49] op_sel_hi:[1,0]
	v_pk_mul_f32 v[30:31], v[30:31], v[48:49] op_sel_hi:[1,0]
	v_pk_mul_f32 v[32:33], v[32:33], v[48:49] op_sel_hi:[1,0]
	v_pk_mul_f32 v[34:35], v[34:35], v[48:49] op_sel_hi:[1,0]
	v_pk_mul_f32 v[36:37], v[36:37], v[48:49] op_sel_hi:[1,0]
	v_pk_mul_f32 v[38:39], v[38:39], v[48:49] op_sel_hi:[1,0]
	v_pk_mul_f32 v[40:41], v[40:41], v[48:49] op_sel_hi:[1,0]
	v_pk_mul_f32 v[42:43], v[42:43], v[48:49] op_sel_hi:[1,0]
	v_pk_mul_f32 v[44:45], v[44:45], v[48:49] op_sel_hi:[1,0]
	v_pk_mul_f32 v[46:47], v[46:47], v[48:49] op_sel_hi:[1,0]
	v_pk_mul_f32 v[16:17], v[16:17], v[148:149]
	v_pk_mul_f32 v[18:19], v[18:19], v[150:151]
	v_pk_mul_f32 v[20:21], v[20:21], v[152:153]
	v_pk_mul_f32 v[22:23], v[22:23], v[154:155]
	v_pk_mul_f32 v[24:25], v[24:25], v[156:157]
	v_pk_mul_f32 v[26:27], v[26:27], v[158:159]
	v_pk_mul_f32 v[28:29], v[28:29], v[160:161]
	v_pk_mul_f32 v[30:31], v[30:31], v[162:163]
	v_pk_mul_f32 v[32:33], v[32:33], v[164:165]
	v_pk_mul_f32 v[34:35], v[34:35], v[166:167]
	v_pk_mul_f32 v[36:37], v[36:37], v[168:169]
	v_pk_mul_f32 v[38:39], v[38:39], v[170:171]
	v_pk_mul_f32 v[40:41], v[40:41], v[176:177]
	v_pk_mul_f32 v[42:43], v[42:43], v[178:179]
	v_pk_mul_f32 v[44:45], v[44:45], v[180:181]
	v_pk_mul_f32 v[46:47], v[46:47], v[182:183]
	v_mov_b32_e32 v60, v16
	v_mov_b32_e32 v61, v16
	s_nop 1
	v_permlane32_swap_b32_e32 v60, v61
	v_cndmask_b32_e64 v52, v61, v60, s[66:67]
	v_mov_b32_e32 v60, v17
	v_mov_b32_e32 v61, v17
	s_nop 1
	v_permlane32_swap_b32_e32 v60, v61
	v_cndmask_b32_e64 v53, v61, v60, s[66:67]
	v_mov_b32_e32 v60, v18
	v_mov_b32_e32 v61, v18
	s_nop 1
	v_permlane32_swap_b32_e32 v60, v61
	v_cndmask_b32_e64 v54, v61, v60, s[66:67]
	v_mov_b32_e32 v60, v19
	v_mov_b32_e32 v61, v19
	s_nop 1
	v_permlane32_swap_b32_e32 v60, v61
	v_cndmask_b32_e64 v55, v61, v60, s[66:67]
	v_mov_b32_e32 v60, v20
	v_mov_b32_e32 v61, v20
	s_nop 1
	v_permlane32_swap_b32_e32 v60, v61
	v_cndmask_b32_e64 v56, v61, v60, s[66:67]
	v_mov_b32_e32 v60, v21
	v_mov_b32_e32 v61, v21
	s_nop 1
	v_permlane32_swap_b32_e32 v60, v61
	v_cndmask_b32_e64 v57, v61, v60, s[66:67]
	v_mov_b32_e32 v60, v22
	v_mov_b32_e32 v61, v22
	s_nop 1
	v_permlane32_swap_b32_e32 v60, v61
	v_cndmask_b32_e64 v58, v61, v60, s[66:67]
	v_mov_b32_e32 v60, v23
	v_mov_b32_e32 v61, v23
	s_nop 1
	v_permlane32_swap_b32_e32 v60, v61
	v_cndmask_b32_e64 v59, v61, v60, s[66:67]
	v_mul_f32_e32 v52, v52, v133
	v_mul_f32_e32 v53, v53, v135
	v_mul_f32_e32 v54, v54, v137
	v_mul_f32_e32 v55, v55, v139
	v_mul_f32_e32 v56, v56, v141
	v_mul_f32_e32 v57, v57, v143
	v_mul_f32_e32 v58, v58, v145
	v_mul_f32_e32 v59, v59, v147
	v_cndmask_b32_e64 v52, -v52, v52, s[66:67]
	v_cndmask_b32_e64 v53, -v53, v53, s[66:67]
	v_cndmask_b32_e64 v54, -v54, v54, s[66:67]
	v_cndmask_b32_e64 v55, -v55, v55, s[66:67]
	v_cndmask_b32_e64 v56, -v56, v56, s[66:67]
	v_cndmask_b32_e64 v57, -v57, v57, s[66:67]
	v_cndmask_b32_e64 v58, -v58, v58, s[66:67]
	v_cndmask_b32_e64 v59, -v59, v59, s[66:67]
	v_fma_f32 v16, v16, v132, v52
	v_fma_f32 v17, v17, v134, v53
	v_fma_f32 v18, v18, v136, v54
	v_fma_f32 v19, v19, v138, v55
	v_fma_f32 v20, v20, v140, v56
	v_fma_f32 v21, v21, v142, v57
	v_fma_f32 v22, v22, v144, v58
	v_fma_f32 v23, v23, v146, v59
	v_pk_mul_f32 v[16:17], v[16:17], v[50:51] op_sel_hi:[1,0]
	v_pk_mul_f32 v[18:19], v[18:19], v[50:51] op_sel_hi:[1,0]
	v_pk_mul_f32 v[20:21], v[20:21], v[50:51] op_sel_hi:[1,0]
	v_pk_mul_f32 v[22:23], v[22:23], v[50:51] op_sel_hi:[1,0]
	v_pk_mul_f32 v[24:25], v[24:25], v[50:51] op_sel_hi:[1,0]
	v_pk_mul_f32 v[26:27], v[26:27], v[50:51] op_sel_hi:[1,0]
	v_pk_mul_f32 v[28:29], v[28:29], v[50:51] op_sel_hi:[1,0]
	v_pk_mul_f32 v[30:31], v[30:31], v[50:51] op_sel_hi:[1,0]
	v_pk_mul_f32 v[32:33], v[32:33], v[50:51] op_sel_hi:[1,0]
	v_pk_mul_f32 v[34:35], v[34:35], v[50:51] op_sel_hi:[1,0]
	v_pk_mul_f32 v[36:37], v[36:37], v[50:51] op_sel_hi:[1,0]
	v_pk_mul_f32 v[38:39], v[38:39], v[50:51] op_sel_hi:[1,0]
	v_pk_mul_f32 v[40:41], v[40:41], v[50:51] op_sel_hi:[1,0]
	v_pk_mul_f32 v[42:43], v[42:43], v[50:51] op_sel_hi:[1,0]
	v_pk_mul_f32 v[44:45], v[44:45], v[50:51] op_sel_hi:[1,0]
	v_pk_mul_f32 v[46:47], v[46:47], v[50:51] op_sel_hi:[1,0]
	v_cvt_pk_bf16_f32 v132, v16, v17
	v_cvt_pk_bf16_f32 v133, v18, v19
	v_cvt_pk_bf16_f32 v134, v20, v21
	v_cvt_pk_bf16_f32 v135, v22, v23
	v_cvt_pk_bf16_f32 v136, v24, v25
	v_cvt_pk_bf16_f32 v137, v26, v27
	v_cvt_pk_bf16_f32 v138, v28, v29
	v_cvt_pk_bf16_f32 v139, v30, v31
	v_cvt_pk_bf16_f32 v140, v32, v33
	v_cvt_pk_bf16_f32 v141, v34, v35
	v_cvt_pk_bf16_f32 v142, v36, v37
	v_cvt_pk_bf16_f32 v143, v38, v39
	v_cvt_pk_bf16_f32 v144, v40, v41
	v_cvt_pk_bf16_f32 v145, v42, v43
	v_cvt_pk_bf16_f32 v146, v44, v45
	v_cvt_pk_bf16_f32 v147, v46, v47
.Lat_qdone:
	v_mov_b32_e32 v234, v212
	v_mov_b32_e32 v235, v212
	v_mov_b32_e32 v236, v212
	v_mov_b32_e32 v237, v212
	v_mov_b32_e32 v238, v212
	v_mov_b32_e32 v239, v212
	v_mov_b32_e32 v240, v212
	v_mov_b32_e32 v241, v212
	v_mov_b32_e32 v242, v212
	v_mov_b32_e32 v243, v212
	v_mov_b32_e32 v244, v212
	v_mov_b32_e32 v245, v212
	v_mov_b32_e32 v246, v212
	v_mov_b32_e32 v247, v212
	v_mov_b32_e32 v248, v212
	v_mov_b32_e32 v249, v212
	v_mov_b32_e32 v192, v212
	v_mov_b32_e32 v193, v212
	v_mov_b32_e32 v194, v212
	v_mov_b32_e32 v195, v212
	v_mov_b32_e32 v196, v212
	v_mov_b32_e32 v197, v212
	v_mov_b32_e32 v198, v212
	v_mov_b32_e32 v199, v212
	v_mov_b32_e32 v200, v212
	v_mov_b32_e32 v201, v212
	v_mov_b32_e32 v202, v212
	v_mov_b32_e32 v203, v212
	v_mov_b32_e32 v204, v212
	v_mov_b32_e32 v205, v212
	v_mov_b32_e32 v206, v212
	v_mov_b32_e32 v207, v212
	v_mov_b32_e32 v16, 0
	v_mov_b32_e32 v17, 0
	v_mov_b32_e32 v18, 0
	v_mov_b32_e32 v19, 0
	v_mov_b32_e32 v20, 0
	v_mov_b32_e32 v21, 0
	v_mov_b32_e32 v22, 0
	v_mov_b32_e32 v23, 0
	v_mov_b32_e32 v24, 0
	v_mov_b32_e32 v25, 0
	v_mov_b32_e32 v26, 0
	v_mov_b32_e32 v27, 0
	v_mov_b32_e32 v28, 0
	v_mov_b32_e32 v29, 0
	v_mov_b32_e32 v30, 0
	v_mov_b32_e32 v31, 0
	v_mov_b32_e32 v32, 0
	v_mov_b32_e32 v33, 0
	v_mov_b32_e32 v34, 0
	v_mov_b32_e32 v35, 0
	v_mov_b32_e32 v36, 0
	v_mov_b32_e32 v37, 0
	v_mov_b32_e32 v38, 0
	v_mov_b32_e32 v39, 0
	v_mov_b32_e32 v40, 0
	v_mov_b32_e32 v41, 0
	v_mov_b32_e32 v42, 0
	v_mov_b32_e32 v43, 0
	v_mov_b32_e32 v44, 0
	v_mov_b32_e32 v45, 0
	v_mov_b32_e32 v46, 0
	v_mov_b32_e32 v47, 0
	v_mov_b32_e32 v48, 0
	v_mov_b32_e32 v49, 0
	v_mov_b32_e32 v50, 0
	v_mov_b32_e32 v51, 0
	v_mov_b32_e32 v52, 0
	v_mov_b32_e32 v53, 0
	v_mov_b32_e32 v54, 0
	v_mov_b32_e32 v55, 0
	v_mov_b32_e32 v56, 0
	v_mov_b32_e32 v57, 0
	v_mov_b32_e32 v58, 0
	v_mov_b32_e32 v59, 0
	v_mov_b32_e32 v60, 0
	v_mov_b32_e32 v61, 0
	v_mov_b32_e32 v62, 0
	v_mov_b32_e32 v63, 0
	v_mov_b32_e32 v64, 0
	v_mov_b32_e32 v65, 0
	v_mov_b32_e32 v66, 0
	v_mov_b32_e32 v67, 0
	v_mov_b32_e32 v68, 0
	v_mov_b32_e32 v69, 0
	v_mov_b32_e32 v70, 0
	v_mov_b32_e32 v71, 0
	v_mov_b32_e32 v72, 0
	v_mov_b32_e32 v73, 0
	v_mov_b32_e32 v74, 0
	v_mov_b32_e32 v75, 0
	v_mov_b32_e32 v76, 0
	v_mov_b32_e32 v77, 0
	v_mov_b32_e32 v78, 0
	v_mov_b32_e32 v79, 0
.Lat_bar2:
	s_barrier
	s_mov_b32 s57, 0
	s_mov_b32 s58, s70
	v_mov_b32_e32 v216, v8
	v_mov_b32_e32 v217, v9
.Lat_jloop_7:
	s_cmp_lt_u32 s58, s68
	s_cbranch_scc1 .Lat_jnext_8
	s_cmp_ge_u32 s58, s69
	s_cbranch_scc1 .Lat_jnext_8
	ds_read_b128 v[148:151], v216 offset:0
	ds_read_b128 v[152:155], v216 offset:32
	ds_read_b128 v[156:159], v216 offset:64
	ds_read_b128 v[160:163], v216 offset:96
	ds_read_b64_tr_b16 v[176:177], v217 offset:0
	ds_read_b64_tr_b16 v[178:179], v217 offset:1152
	ds_read_b64_tr_b16 v[180:181], v217 offset:2304
	ds_read_b64_tr_b16 v[182:183], v217 offset:3456
	ds_read_b64_tr_b16 v[184:185], v217 offset:64
	ds_read_b64_tr_b16 v[186:187], v217 offset:1216
	ds_read_b64_tr_b16 v[188:189], v217 offset:2368
	ds_read_b64_tr_b16 v[190:191], v217 offset:3520
	s_cmp_eq_u32 s57, 9
	s_cbranch_scc1 .Lat_t1only_9
	s_cmp_eq_u32 s57, 0
	s_cbranch_scc1 .Lat_t0only_10
	s_waitcnt lgkmcnt(8)
	v_mfma_f32_32x32x16_bf16 v[80:95], v[148:151], v[116:119], v[234:249]
	v_mfma_f32_32x32x16_bf16 v[80:95], v[152:155], v[120:123], v[80:95]
	v_mfma_f32_32x32x16_bf16 v[80:95], v[156:159], v[124:127], v[80:95]
	v_mfma_f32_32x32x16_bf16 v[80:95], v[160:163], v[128:131], v[80:95]
	v_mfma_f32_32x32x16_bf16 v[96:111], v[148:151], v[132:135], v[192:207]
	v_mfma_f32_32x32x16_bf16 v[96:111], v[152:155], v[136:139], v[96:111]
	v_mfma_f32_32x32x16_bf16 v[96:111], v[156:159], v[140:143], v[96:111]
	v_mfma_f32_32x32x16_bf16 v[96:111], v[160:163], v[144:147], v[96:111]
	s_cmp_eq_u32 s57, 0
	s_cbranch_scc0 .Lat_nolo_11
	v_cmp_lt_i32_e64 s[74:75], 0, v15
	v_cmp_lt_i32_e64 s[76:77], 1, v15
	v_cmp_lt_i32_e64 s[78:79], 2, v15
	v_cmp_lt_i32_e64 s[80:81], 3, v15
	v_cndmask_b32_e64 v80, v80, v232, s[74:75]
	v_cndmask_b32_e64 v81, v81, v232, s[76:77]
	v_cndmask_b32_e64 v82, v82, v232, s[78:79]
	v_cndmask_b32_e64 v83, v83, v232, s[80:81]
	v_cmp_lt_i32_e64 s[74:75], 8, v15
	v_cmp_lt_i32_e64 s[76:77], 9, v15
	v_cmp_lt_i32_e64 s[78:79], 10, v15
	v_cmp_lt_i32_e64 s[80:81], 11, v15
	v_cndmask_b32_e64 v84, v84, v232, s[74:75]
	v_cndmask_b32_e64 v85, v85, v232, s[76:77]
	v_cndmask_b32_e64 v86, v86, v232, s[78:79]
	v_cndmask_b32_e64 v87, v87, v232, s[80:81]
	v_cmp_lt_i32_e64 s[74:75], 16, v15
	v_cmp_lt_i32_e64 s[76:77], 17, v15
	v_cmp_lt_i32_e64 s[78:79], 18, v15
	v_cmp_lt_i32_e64 s[80:81], 19, v15
	v_cndmask_b32_e64 v88, v88, v232, s[74:75]
	v_cndmask_b32_e64 v89, v89, v232, s[76:77]
	v_cndmask_b32_e64 v90, v90, v232, s[78:79]
	v_cndmask_b32_e64 v91, v91, v232, s[80:81]
	v_cmp_lt_i32_e64 s[74:75], 24, v15
	v_cmp_lt_i32_e64 s[76:77], 25, v15
	v_cmp_lt_i32_e64 s[78:79], 26, v15
	v_cmp_lt_i32_e64 s[80:81], 27, v15
	v_cndmask_b32_e64 v92, v92, v232, s[74:75]
	v_cndmask_b32_e64 v93, v93, v232, s[76:77]
	v_cndmask_b32_e64 v94, v94, v232, s[78:79]
	v_cndmask_b32_e64 v95, v95, v232, s[80:81]
.Lat_nolo_11:
	s_cmp_eq_u32 s57, 8
	s_cbranch_scc0 .Lat_nohi_12
	v_cmp_gt_i32_e64 s[74:75], 0, v15
	v_cmp_gt_i32_e64 s[76:77], 1, v15
	v_cmp_gt_i32_e64 s[78:79], 2, v15
	v_cmp_gt_i32_e64 s[80:81], 3, v15
	v_cndmask_b32_e64 v80, v80, v232, s[74:75]
	v_cndmask_b32_e64 v81, v81, v232, s[76:77]
	v_cndmask_b32_e64 v82, v82, v232, s[78:79]
	v_cndmask_b32_e64 v83, v83, v232, s[80:81]
	v_cmp_gt_i32_e64 s[74:75], 8, v15
	v_cmp_gt_i32_e64 s[76:77], 9, v15
	v_cmp_gt_i32_e64 s[78:79], 10, v15
	v_cmp_gt_i32_e64 s[80:81], 11, v15
	v_cndmask_b32_e64 v84, v84, v232, s[74:75]
	v_cndmask_b32_e64 v85, v85, v232, s[76:77]
	v_cndmask_b32_e64 v86, v86, v232, s[78:79]
	v_cndmask_b32_e64 v87, v87, v232, s[80:81]
	v_cmp_gt_i32_e64 s[74:75], 16, v15
	v_cmp_gt_i32_e64 s[76:77], 17, v15
	v_cmp_gt_i32_e64 s[78:79], 18, v15
	v_cmp_gt_i32_e64 s[80:81], 19, v15
	v_cndmask_b32_e64 v88, v88, v232, s[74:75]
	v_cndmask_b32_e64 v89, v89, v232, s[76:77]
	v_cndmask_b32_e64 v90, v90, v232, s[78:79]
	v_cndmask_b32_e64 v91, v91, v232, s[80:81]
	v_cmp_gt_i32_e64 s[74:75], 24, v15
	v_cmp_gt_i32_e64 s[76:77], 25, v15
	v_cmp_gt_i32_e64 s[78:79], 26, v15
	v_cmp_gt_i32_e64 s[80:81], 27, v15
	v_cndmask_b32_e64 v92, v92, v232, s[74:75]
	v_cndmask_b32_e64 v93, v93, v232, s[76:77]
	v_cndmask_b32_e64 v94, v94, v232, s[78:79]
	v_cndmask_b32_e64 v95, v95, v232, s[80:81]
.Lat_nohi_12:
	v_max3_f32 v212, v80, v81, v82
	v_max3_f32 v250, v83, v84, v85
	v_max3_f32 v212, v212, v86, v87
	v_max3_f32 v250, v250, v88, v89
	v_max3_f32 v212, v212, v90, v91
	v_max3_f32 v250, v250, v92, v93
	v_max3_f32 v212, v212, v94, v95
	v_max_f32_e32 v212, v212, v250
	v_mov_b32_e32 v250, v212
	s_nop 1
	v_permlane32_swap_b32_e32 v212, v250
	v_max_f32_e32 v212, v212, v250
	v_cmp_lt_f32_e32 vcc, 0x41000000, v212
	s_cbranch_vccz .Lat_nors_13
	v_max_f32_e32 v212, 0, v212
	v_exp_f32_e64 v172, -v212
	v_sub_f32_e32 v80, v80, v212
	v_sub_f32_e32 v81, v81, v212
	v_sub_f32_e32 v82, v82, v212
	v_sub_f32_e32 v83, v83, v212
	v_sub_f32_e32 v84, v84, v212
	v_sub_f32_e32 v85, v85, v212
	v_sub_f32_e32 v86, v86, v212
	v_sub_f32_e32 v87, v87, v212
	v_sub_f32_e32 v88, v88, v212
	v_sub_f32_e32 v89, v89, v212
	v_sub_f32_e32 v90, v90, v212
	v_sub_f32_e32 v91, v91, v212
	v_sub_f32_e32 v92, v92, v212
	v_sub_f32_e32 v93, v93, v212
	v_sub_f32_e32 v94, v94, v212
	v_sub_f32_e32 v95, v95, v212
	v_sub_f32_e32 v234, v234, v212
	v_sub_f32_e32 v235, v235, v212
	v_sub_f32_e32 v236, v236, v212
	v_sub_f32_e32 v237, v237, v212
	v_sub_f32_e32 v238, v238, v212
	v_sub_f32_e32 v239, v239, v212
	v_sub_f32_e32 v240, v240, v212
	v_sub_f32_e32 v241, v241, v212
	v_sub_f32_e32 v242, v242, v212
	v_sub_f32_e32 v243, v243, v212
	v_sub_f32_e32 v244, v244, v212
	v_sub_f32_e32 v245, v245, v212
	v_sub_f32_e32 v246, v246, v212
	v_sub_f32_e32 v247, v247, v212
	v_sub_f32_e32 v248, v248, v212
	v_sub_f32_e32 v249, v249, v212
	v_mul_f32_e32 v209, v209, v172
	v_mul_f32_e32 v16, v16, v172
	v_mul_f32_e32 v17, v17, v172
	v_mul_f32_e32 v18, v18, v172
	v_mul_f32_e32 v19, v19, v172
	v_mul_f32_e32 v20, v20, v172
	v_mul_f32_e32 v21, v21, v172
	v_mul_f32_e32 v22, v22, v172
	v_mul_f32_e32 v23, v23, v172
	v_mul_f32_e32 v24, v24, v172
	v_mul_f32_e32 v25, v25, v172
	v_mul_f32_e32 v26, v26, v172
	v_mul_f32_e32 v27, v27, v172
	v_mul_f32_e32 v28, v28, v172
	v_mul_f32_e32 v29, v29, v172
	v_mul_f32_e32 v30, v30, v172
	v_mul_f32_e32 v31, v31, v172
	v_mul_f32_e32 v32, v32, v172
	v_mul_f32_e32 v33, v33, v172
	v_mul_f32_e32 v34, v34, v172
	v_mul_f32_e32 v35, v35, v172
	v_mul_f32_e32 v36, v36, v172
	v_mul_f32_e32 v37, v37, v172
	v_mul_f32_e32 v38, v38, v172
	v_mul_f32_e32 v39, v39, v172
	v_mul_f32_e32 v40, v40, v172
	v_mul_f32_e32 v41, v41, v172
	v_mul_f32_e32 v42, v42, v172
	v_mul_f32_e32 v43, v43, v172
	v_mul_f32_e32 v44, v44, v172
	v_mul_f32_e32 v45, v45, v172
	v_mul_f32_e32 v46, v46, v172
	v_mul_f32_e32 v47, v47, v172
.Lat_nors_13:
	v_exp_f32_e32 v80, v80
	v_exp_f32_e32 v81, v81
	v_exp_f32_e32 v82, v82
	v_exp_f32_e32 v83, v83
	v_exp_f32_e32 v84, v84
	v_exp_f32_e32 v85, v85
	v_exp_f32_e32 v86, v86
	v_exp_f32_e32 v87, v87
	v_exp_f32_e32 v88, v88
	v_exp_f32_e32 v89, v89
	v_exp_f32_e32 v90, v90
	v_exp_f32_e32 v91, v91
	v_exp_f32_e32 v92, v92
	v_exp_f32_e32 v93, v93
	v_exp_f32_e32 v94, v94
	v_exp_f32_e32 v95, v95
	v_cvt_pk_bf16_f32 v164, v80, v81
	v_cvt_pk_bf16_f32 v165, v82, v83
	v_cvt_pk_bf16_f32 v166, v84, v85
	v_cvt_pk_bf16_f32 v167, v86, v87
	v_cvt_pk_bf16_f32 v168, v88, v89
	v_cvt_pk_bf16_f32 v169, v90, v91
	v_cvt_pk_bf16_f32 v170, v92, v93
	v_cvt_pk_bf16_f32 v171, v94, v95
	s_waitcnt lgkmcnt(0)
	v_mfma_f32_32x32x16_bf16 v[16:31], v[176:179], v[164:167], v[16:31]
	v_mfma_f32_32x32x16_bf16 v[32:47], v[184:187], v[164:167], v[32:47]
	v_mfma_f32_32x32x16_bf16 v[16:31], v[180:183], v[168:171], v[16:31]
	v_mfma_f32_32x32x16_bf16 v[32:47], v[188:191], v[168:171], v[32:47]
	v_add_f32_e32 v212, v80, v81
	v_add_f32_e32 v250, v82, v83
	v_add_f32_e32 v212, v212, v84
	v_add_f32_e32 v250, v250, v85
	v_add_f32_e32 v212, v212, v86
	v_add_f32_e32 v250, v250, v87
	v_add_f32_e32 v212, v212, v88
	v_add_f32_e32 v250, v250, v89
	v_add_f32_e32 v212, v212, v90
	v_add_f32_e32 v250, v250, v91
	v_add_f32_e32 v212, v212, v92
	v_add_f32_e32 v250, v250, v93
	v_add_f32_e32 v212, v212, v94
	v_add_f32_e32 v250, v250, v95
	v_add_f32_e32 v212, v212, v250
	v_add_f32_e32 v209, v209, v212
	s_cmp_eq_u32 s57, 1
	s_cbranch_scc0 .Lat_nolo_14
	v_cmp_lt_i32_e64 s[74:75], 0, v15
	v_cmp_lt_i32_e64 s[76:77], 1, v15
	v_cmp_lt_i32_e64 s[78:79], 2, v15
	v_cmp_lt_i32_e64 s[80:81], 3, v15
	v_cndmask_b32_e64 v96, v96, v232, s[74:75]
	v_cndmask_b32_e64 v97, v97, v232, s[76:77]
	v_cndmask_b32_e64 v98, v98, v232, s[78:79]
	v_cndmask_b32_e64 v99, v99, v232, s[80:81]
	v_cmp_lt_i32_e64 s[74:75], 8, v15
	v_cmp_lt_i32_e64 s[76:77], 9, v15
	v_cmp_lt_i32_e64 s[78:79], 10, v15
	v_cmp_lt_i32_e64 s[80:81], 11, v15
	v_cndmask_b32_e64 v100, v100, v232, s[74:75]
	v_cndmask_b32_e64 v101, v101, v232, s[76:77]
	v_cndmask_b32_e64 v102, v102, v232, s[78:79]
	v_cndmask_b32_e64 v103, v103, v232, s[80:81]
	v_cmp_lt_i32_e64 s[74:75], 16, v15
	v_cmp_lt_i32_e64 s[76:77], 17, v15
	v_cmp_lt_i32_e64 s[78:79], 18, v15
	v_cmp_lt_i32_e64 s[80:81], 19, v15
	v_cndmask_b32_e64 v104, v104, v232, s[74:75]
	v_cndmask_b32_e64 v105, v105, v232, s[76:77]
	v_cndmask_b32_e64 v106, v106, v232, s[78:79]
	v_cndmask_b32_e64 v107, v107, v232, s[80:81]
	v_cmp_lt_i32_e64 s[74:75], 24, v15
	v_cmp_lt_i32_e64 s[76:77], 25, v15
	v_cmp_lt_i32_e64 s[78:79], 26, v15
	v_cmp_lt_i32_e64 s[80:81], 27, v15
	v_cndmask_b32_e64 v108, v108, v232, s[74:75]
	v_cndmask_b32_e64 v109, v109, v232, s[76:77]
	v_cndmask_b32_e64 v110, v110, v232, s[78:79]
	v_cndmask_b32_e64 v111, v111, v232, s[80:81]
.Lat_nolo_14:
	s_cmp_eq_u32 s57, 9
	s_cbranch_scc0 .Lat_nohi_15
	v_cmp_gt_i32_e64 s[74:75], 0, v15
	v_cmp_gt_i32_e64 s[76:77], 1, v15
	v_cmp_gt_i32_e64 s[78:79], 2, v15
	v_cmp_gt_i32_e64 s[80:81], 3, v15
	v_cndmask_b32_e64 v96, v96, v232, s[74:75]
	v_cndmask_b32_e64 v97, v97, v232, s[76:77]
	v_cndmask_b32_e64 v98, v98, v232, s[78:79]
	v_cndmask_b32_e64 v99, v99, v232, s[80:81]
	v_cmp_gt_i32_e64 s[74:75], 8, v15
	v_cmp_gt_i32_e64 s[76:77], 9, v15
	v_cmp_gt_i32_e64 s[78:79], 10, v15
	v_cmp_gt_i32_e64 s[80:81], 11, v15
	v_cndmask_b32_e64 v100, v100, v232, s[74:75]
	v_cndmask_b32_e64 v101, v101, v232, s[76:77]
	v_cndmask_b32_e64 v102, v102, v232, s[78:79]
	v_cndmask_b32_e64 v103, v103, v232, s[80:81]
	v_cmp_gt_i32_e64 s[74:75], 16, v15
	v_cmp_gt_i32_e64 s[76:77], 17, v15
	v_cmp_gt_i32_e64 s[78:79], 18, v15
	v_cmp_gt_i32_e64 s[80:81], 19, v15
	v_cndmask_b32_e64 v104, v104, v232, s[74:75]
	v_cndmask_b32_e64 v105, v105, v232, s[76:77]
	v_cndmask_b32_e64 v106, v106, v232, s[78:79]
	v_cndmask_b32_e64 v107, v107, v232, s[80:81]
	v_cmp_gt_i32_e64 s[74:75], 24, v15
	v_cmp_gt_i32_e64 s[76:77], 25, v15
	v_cmp_gt_i32_e64 s[78:79], 26, v15
	v_cmp_gt_i32_e64 s[80:81], 27, v15
	v_cndmask_b32_e64 v108, v108, v232, s[74:75]
	v_cndmask_b32_e64 v109, v109, v232, s[76:77]
	v_cndmask_b32_e64 v110, v110, v232, s[78:79]
	v_cndmask_b32_e64 v111, v111, v232, s[80:81]
.Lat_nohi_15:
	v_max3_f32 v212, v96, v97, v98
	v_max3_f32 v250, v99, v100, v101
	v_max3_f32 v212, v212, v102, v103
	v_max3_f32 v250, v250, v104, v105
	v_max3_f32 v212, v212, v106, v107
	v_max3_f32 v250, v250, v108, v109
	v_max3_f32 v212, v212, v110, v111
	v_max_f32_e32 v212, v212, v250
	v_mov_b32_e32 v250, v212
	s_nop 1
	v_permlane32_swap_b32_e32 v212, v250
	v_max_f32_e32 v212, v212, v250
	v_cmp_lt_f32_e32 vcc, 0x41000000, v212
	s_cbranch_vccz .Lat_nors_16
	v_max_f32_e32 v212, 0, v212
	v_exp_f32_e64 v172, -v212
	v_sub_f32_e32 v96, v96, v212
	v_sub_f32_e32 v97, v97, v212
	v_sub_f32_e32 v98, v98, v212
	v_sub_f32_e32 v99, v99, v212
	v_sub_f32_e32 v100, v100, v212
	v_sub_f32_e32 v101, v101, v212
	v_sub_f32_e32 v102, v102, v212
	v_sub_f32_e32 v103, v103, v212
	v_sub_f32_e32 v104, v104, v212
	v_sub_f32_e32 v105, v105, v212
	v_sub_f32_e32 v106, v106, v212
	v_sub_f32_e32 v107, v107, v212
	v_sub_f32_e32 v108, v108, v212
	v_sub_f32_e32 v109, v109, v212
	v_sub_f32_e32 v110, v110, v212
	v_sub_f32_e32 v111, v111, v212
	v_sub_f32_e32 v192, v192, v212
	v_sub_f32_e32 v193, v193, v212
	v_sub_f32_e32 v194, v194, v212
	v_sub_f32_e32 v195, v195, v212
	v_sub_f32_e32 v196, v196, v212
	v_sub_f32_e32 v197, v197, v212
	v_sub_f32_e32 v198, v198, v212
	v_sub_f32_e32 v199, v199, v212
	v_sub_f32_e32 v200, v200, v212
	v_sub_f32_e32 v201, v201, v212
	v_sub_f32_e32 v202, v202, v212
	v_sub_f32_e32 v203, v203, v212
	v_sub_f32_e32 v204, v204, v212
	v_sub_f32_e32 v205, v205, v212
	v_sub_f32_e32 v206, v206, v212
	v_sub_f32_e32 v207, v207, v212
	v_mul_f32_e32 v211, v211, v172
	v_mul_f32_e32 v48, v48, v172
	v_mul_f32_e32 v49, v49, v172
	v_mul_f32_e32 v50, v50, v172
	v_mul_f32_e32 v51, v51, v172
	v_mul_f32_e32 v52, v52, v172
	v_mul_f32_e32 v53, v53, v172
	v_mul_f32_e32 v54, v54, v172
	v_mul_f32_e32 v55, v55, v172
	v_mul_f32_e32 v56, v56, v172
	v_mul_f32_e32 v57, v57, v172
	v_mul_f32_e32 v58, v58, v172
	v_mul_f32_e32 v59, v59, v172
	v_mul_f32_e32 v60, v60, v172
	v_mul_f32_e32 v61, v61, v172
	v_mul_f32_e32 v62, v62, v172
	v_mul_f32_e32 v63, v63, v172
	v_mul_f32_e32 v64, v64, v172
	v_mul_f32_e32 v65, v65, v172
	v_mul_f32_e32 v66, v66, v172
	v_mul_f32_e32 v67, v67, v172
	v_mul_f32_e32 v68, v68, v172
	v_mul_f32_e32 v69, v69, v172
	v_mul_f32_e32 v70, v70, v172
	v_mul_f32_e32 v71, v71, v172
	v_mul_f32_e32 v72, v72, v172
	v_mul_f32_e32 v73, v73, v172
	v_mul_f32_e32 v74, v74, v172
	v_mul_f32_e32 v75, v75, v172
	v_mul_f32_e32 v76, v76, v172
	v_mul_f32_e32 v77, v77, v172
	v_mul_f32_e32 v78, v78, v172
	v_mul_f32_e32 v79, v79, v172
.Lat_nors_16:
	v_exp_f32_e32 v96, v96
	v_exp_f32_e32 v97, v97
	v_exp_f32_e32 v98, v98
	v_exp_f32_e32 v99, v99
	v_exp_f32_e32 v100, v100
	v_exp_f32_e32 v101, v101
	v_exp_f32_e32 v102, v102
	v_exp_f32_e32 v103, v103
	v_exp_f32_e32 v104, v104
	v_exp_f32_e32 v105, v105
	v_exp_f32_e32 v106, v106
	v_exp_f32_e32 v107, v107
	v_exp_f32_e32 v108, v108
	v_exp_f32_e32 v109, v109
	v_exp_f32_e32 v110, v110
	v_exp_f32_e32 v111, v111
	v_cvt_pk_bf16_f32 v164, v96, v97
	v_cvt_pk_bf16_f32 v165, v98, v99
	v_cvt_pk_bf16_f32 v166, v100, v101
	v_cvt_pk_bf16_f32 v167, v102, v103
	v_cvt_pk_bf16_f32 v168, v104, v105
	v_cvt_pk_bf16_f32 v169, v106, v107
	v_cvt_pk_bf16_f32 v170, v108, v109
	v_cvt_pk_bf16_f32 v171, v110, v111
	s_waitcnt lgkmcnt(0)
	v_mfma_f32_32x32x16_bf16 v[48:63], v[176:179], v[164:167], v[48:63]
	v_mfma_f32_32x32x16_bf16 v[64:79], v[184:187], v[164:167], v[64:79]
	v_mfma_f32_32x32x16_bf16 v[48:63], v[180:183], v[168:171], v[48:63]
	v_mfma_f32_32x32x16_bf16 v[64:79], v[188:191], v[168:171], v[64:79]
	v_add_f32_e32 v212, v96, v97
	v_add_f32_e32 v250, v98, v99
	v_add_f32_e32 v212, v212, v100
	v_add_f32_e32 v250, v250, v101
	v_add_f32_e32 v212, v212, v102
	v_add_f32_e32 v250, v250, v103
	v_add_f32_e32 v212, v212, v104
	v_add_f32_e32 v250, v250, v105
	v_add_f32_e32 v212, v212, v106
	v_add_f32_e32 v250, v250, v107
	v_add_f32_e32 v212, v212, v108
	v_add_f32_e32 v250, v250, v109
	v_add_f32_e32 v212, v212, v110
	v_add_f32_e32 v250, v250, v111
	v_add_f32_e32 v212, v212, v250
	v_add_f32_e32 v211, v211, v212
	s_branch .Lat_jnext_8
.Lat_t0only_10:
	s_waitcnt lgkmcnt(8)
	v_mfma_f32_32x32x16_bf16 v[80:95], v[148:151], v[116:119], v[234:249]
	v_mfma_f32_32x32x16_bf16 v[80:95], v[152:155], v[120:123], v[80:95]
	v_mfma_f32_32x32x16_bf16 v[80:95], v[156:159], v[124:127], v[80:95]
	v_mfma_f32_32x32x16_bf16 v[80:95], v[160:163], v[128:131], v[80:95]
	s_nop 7
	s_nop 7
	s_cmp_eq_u32 s57, 0
	s_cbranch_scc0 .Lat_nolo_17
	v_cmp_lt_i32_e64 s[74:75], 0, v15
	v_cmp_lt_i32_e64 s[76:77], 1, v15
	v_cmp_lt_i32_e64 s[78:79], 2, v15
	v_cmp_lt_i32_e64 s[80:81], 3, v15
	v_cndmask_b32_e64 v80, v80, v232, s[74:75]
	v_cndmask_b32_e64 v81, v81, v232, s[76:77]
	v_cndmask_b32_e64 v82, v82, v232, s[78:79]
	v_cndmask_b32_e64 v83, v83, v232, s[80:81]
	v_cmp_lt_i32_e64 s[74:75], 8, v15
	v_cmp_lt_i32_e64 s[76:77], 9, v15
	v_cmp_lt_i32_e64 s[78:79], 10, v15
	v_cmp_lt_i32_e64 s[80:81], 11, v15
	v_cndmask_b32_e64 v84, v84, v232, s[74:75]
	v_cndmask_b32_e64 v85, v85, v232, s[76:77]
	v_cndmask_b32_e64 v86, v86, v232, s[78:79]
	v_cndmask_b32_e64 v87, v87, v232, s[80:81]
	v_cmp_lt_i32_e64 s[74:75], 16, v15
	v_cmp_lt_i32_e64 s[76:77], 17, v15
	v_cmp_lt_i32_e64 s[78:79], 18, v15
	v_cmp_lt_i32_e64 s[80:81], 19, v15
	v_cndmask_b32_e64 v88, v88, v232, s[74:75]
	v_cndmask_b32_e64 v89, v89, v232, s[76:77]
	v_cndmask_b32_e64 v90, v90, v232, s[78:79]
	v_cndmask_b32_e64 v91, v91, v232, s[80:81]
	v_cmp_lt_i32_e64 s[74:75], 24, v15
	v_cmp_lt_i32_e64 s[76:77], 25, v15
	v_cmp_lt_i32_e64 s[78:79], 26, v15
	v_cmp_lt_i32_e64 s[80:81], 27, v15
	v_cndmask_b32_e64 v92, v92, v232, s[74:75]
	v_cndmask_b32_e64 v93, v93, v232, s[76:77]
	v_cndmask_b32_e64 v94, v94, v232, s[78:79]
	v_cndmask_b32_e64 v95, v95, v232, s[80:81]

.Lat_nors_19:
	v_exp_f32_e32 v80, v80
	v_exp_f32_e32 v81, v81
	v_exp_f32_e32 v82, v82
	v_exp_f32_e32 v83, v83
	v_exp_f32_e32 v84, v84
	v_exp_f32_e32 v85, v85
	v_exp_f32_e32 v86, v86
	v_exp_f32_e32 v87, v87
	v_exp_f32_e32 v88, v88
	v_exp_f32_e32 v89, v89
	v_exp_f32_e32 v90, v90
	v_exp_f32_e32 v91, v91
	v_exp_f32_e32 v92, v92
	v_exp_f32_e32 v93, v93
	v_exp_f32_e32 v94, v94
	v_exp_f32_e32 v95, v95
	v_cvt_pk_bf16_f32 v164, v80, v81
	v_cvt_pk_bf16_f32 v165, v82, v83
	v_cvt_pk_bf16_f32 v166, v84, v85
	v_cvt_pk_bf16_f32 v167, v86, v87
	v_cvt_pk_bf16_f32 v168, v88, v89
	v_cvt_pk_bf16_f32 v169, v90, v91
	v_cvt_pk_bf16_f32 v170, v92, v93
	v_cvt_pk_bf16_f32 v171, v94, v95
	s_waitcnt lgkmcnt(0)
	v_mfma_f32_32x32x16_bf16 v[16:31], v[176:179], v[164:167], v[16:31]
	v_mfma_f32_32x32x16_bf16 v[32:47], v[184:187], v[164:167], v[32:47]
	v_mfma_f32_32x32x16_bf16 v[16:31], v[180:183], v[168:171], v[16:31]
	v_mfma_f32_32x32x16_bf16 v[32:47], v[188:191], v[168:171], v[32:47]
	v_add_f32_e32 v212, v80, v81
	v_add_f32_e32 v250, v82, v83
	v_add_f32_e32 v212, v212, v84
	v_add_f32_e32 v250, v250, v85
	v_add_f32_e32 v212, v212, v86
	v_add_f32_e32 v250, v250, v87
	v_add_f32_e32 v212, v212, v88
	v_add_f32_e32 v250, v250, v89
	v_add_f32_e32 v212, v212, v90
	v_add_f32_e32 v250, v250, v91
	v_add_f32_e32 v212, v212, v92
	v_add_f32_e32 v250, v250, v93
	v_add_f32_e32 v212, v212, v94
	v_add_f32_e32 v250, v250, v95
	v_add_f32_e32 v212, v212, v250
	v_add_f32_e32 v209, v209, v212
	s_branch .Lat_jnext_8
.Lat_t1only_9:
	s_waitcnt lgkmcnt(8)
	v_mfma_f32_32x32x16_bf16 v[96:111], v[148:151], v[132:135], v[192:207]
	v_mfma_f32_32x32x16_bf16 v[96:111], v[152:155], v[136:139], v[96:111]
	v_mfma_f32_32x32x16_bf16 v[96:111], v[156:159], v[140:143], v[96:111]
	v_mfma_f32_32x32x16_bf16 v[96:111], v[160:163], v[144:147], v[96:111]
	s_nop 7
	s_nop 7
	s_cmp_eq_u32 s57, 1
	s_cbranch_scc0 .Lat_nolo_20
	v_cmp_lt_i32_e64 s[74:75], 0, v15
	v_cmp_lt_i32_e64 s[76:77], 1, v15
	v_cmp_lt_i32_e64 s[78:79], 2, v15
	v_cmp_lt_i32_e64 s[80:81], 3, v15
	v_cndmask_b32_e64 v96, v96, v232, s[74:75]
	v_cndmask_b32_e64 v97, v97, v232, s[76:77]
	v_cndmask_b32_e64 v98, v98, v232, s[78:79]
	v_cndmask_b32_e64 v99, v99, v232, s[80:81]
	v_cmp_lt_i32_e64 s[74:75], 8, v15
	v_cmp_lt_i32_e64 s[76:77], 9, v15
	v_cmp_lt_i32_e64 s[78:79], 10, v15
	v_cmp_lt_i32_e64 s[80:81], 11, v15
	v_cndmask_b32_e64 v100, v100, v232, s[74:75]
	v_cndmask_b32_e64 v101, v101, v232, s[76:77]
	v_cndmask_b32_e64 v102, v102, v232, s[78:79]
	v_cndmask_b32_e64 v103, v103, v232, s[80:81]
	v_cmp_lt_i32_e64 s[74:75], 16, v15
	v_cmp_lt_i32_e64 s[76:77], 17, v15
	v_cmp_lt_i32_e64 s[78:79], 18, v15
	v_cmp_lt_i32_e64 s[80:81], 19, v15
	v_cndmask_b32_e64 v104, v104, v232, s[74:75]
	v_cndmask_b32_e64 v105, v105, v232, s[76:77]
	v_cndmask_b32_e64 v106, v106, v232, s[78:79]
	v_cndmask_b32_e64 v107, v107, v232, s[80:81]
	v_cmp_lt_i32_e64 s[74:75], 24, v15
	v_cmp_lt_i32_e64 s[76:77], 25, v15
	v_cmp_lt_i32_e64 s[78:79], 26, v15
	v_cmp_lt_i32_e64 s[80:81], 27, v15
	v_cndmask_b32_e64 v108, v108, v232, s[74:75]
	v_cndmask_b32_e64 v109, v109, v232, s[76:77]
	v_cndmask_b32_e64 v110, v110, v232, s[78:79]
	v_cndmask_b32_e64 v111, v111, v232, s[80:81]

.Lat_nors_22:
	v_exp_f32_e32 v96, v96
	v_exp_f32_e32 v97, v97
	v_exp_f32_e32 v98, v98
	v_exp_f32_e32 v99, v99
	v_exp_f32_e32 v100, v100
	v_exp_f32_e32 v101, v101
	v_exp_f32_e32 v102, v102
	v_exp_f32_e32 v103, v103
	v_exp_f32_e32 v104, v104
	v_exp_f32_e32 v105, v105
	v_exp_f32_e32 v106, v106
	v_exp_f32_e32 v107, v107
	v_exp_f32_e32 v108, v108
	v_exp_f32_e32 v109, v109
	v_exp_f32_e32 v110, v110
	v_exp_f32_e32 v111, v111
	v_cvt_pk_bf16_f32 v164, v96, v97
	v_cvt_pk_bf16_f32 v165, v98, v99
	v_cvt_pk_bf16_f32 v166, v100, v101
	v_cvt_pk_bf16_f32 v167, v102, v103
	v_cvt_pk_bf16_f32 v168, v104, v105
	v_cvt_pk_bf16_f32 v169, v106, v107
	v_cvt_pk_bf16_f32 v170, v108, v109
	v_cvt_pk_bf16_f32 v171, v110, v111
	s_waitcnt lgkmcnt(0)
	v_mfma_f32_32x32x16_bf16 v[48:63], v[176:179], v[164:167], v[48:63]
	v_mfma_f32_32x32x16_bf16 v[64:79], v[184:187], v[164:167], v[64:79]
	v_mfma_f32_32x32x16_bf16 v[48:63], v[180:183], v[168:171], v[48:63]
	v_mfma_f32_32x32x16_bf16 v[64:79], v[188:191], v[168:171], v[64:79]
	v_add_f32_e32 v212, v96, v97
	v_add_f32_e32 v250, v98, v99
	v_add_f32_e32 v212, v212, v100
	v_add_f32_e32 v250, v250, v101
	v_add_f32_e32 v212, v212, v102
	v_add_f32_e32 v250, v250, v103
	v_add_f32_e32 v212, v212, v104
	v_add_f32_e32 v250, v250, v105
	v_add_f32_e32 v212, v212, v106
	v_add_f32_e32 v250, v250, v107
	v_add_f32_e32 v212, v212, v108
	v_add_f32_e32 v250, v250, v109
	v_add_f32_e32 v212, v212, v110
	v_add_f32_e32 v250, v250, v111
	v_add_f32_e32 v212, v212, v250
	v_add_f32_e32 v211, v211, v212
.Lat_jnext_8:
	s_add_u32 s57, s57, 1
	s_add_u32 s58, s58, 32
	v_add_u32_e32 v216, 0x1200, v216
	v_add_u32_e32 v217, 0x1200, v217
	s_cmp_lt_u32 s57, 10
	s_cbranch_scc1 .Lat_jloop_7
.Lat_output:
	s_nop 7
	s_nop 7
	v_mov_b32_e32 v212, v209
	v_mov_b32_e32 v172, v209
	s_nop 1
	v_permlane32_swap_b32_e32 v212, v172
	v_add_f32_e32 v172, v212, v172
	v_rcp_f32_e32 v172, v172
	s_nop 0
	v_mul_f32_e32 v16, v16, v172
	v_mul_f32_e32 v17, v17, v172
	v_mul_f32_e32 v18, v18, v172
	v_mul_f32_e32 v19, v19, v172
	v_mul_f32_e32 v20, v20, v172
	v_mul_f32_e32 v21, v21, v172
	v_mul_f32_e32 v22, v22, v172
	v_mul_f32_e32 v23, v23, v172
	v_mul_f32_e32 v24, v24, v172
	v_mul_f32_e32 v25, v25, v172
	v_mul_f32_e32 v26, v26, v172
	v_mul_f32_e32 v27, v27, v172
	v_mul_f32_e32 v28, v28, v172
	v_mul_f32_e32 v29, v29, v172
	v_mul_f32_e32 v30, v30, v172
	v_mul_f32_e32 v31, v31, v172
	v_mul_f32_e32 v32, v32, v172
	v_mul_f32_e32 v33, v33, v172
	v_mul_f32_e32 v34, v34, v172
	v_mul_f32_e32 v35, v35, v172
	v_mul_f32_e32 v36, v36, v172
	v_mul_f32_e32 v37, v37, v172
	v_mul_f32_e32 v38, v38, v172
	v_mul_f32_e32 v39, v39, v172
	v_mul_f32_e32 v40, v40, v172
	v_mul_f32_e32 v41, v41, v172
	v_mul_f32_e32 v42, v42, v172
	v_mul_f32_e32 v43, v43, v172
	v_mul_f32_e32 v44, v44, v172
	v_mul_f32_e32 v45, v45, v172
	v_mul_f32_e32 v46, v46, v172
	v_mul_f32_e32 v47, v47, v172
	v_cvt_pk_bf16_f32 v164, v16, v17
	v_cvt_pk_bf16_f32 v165, v18, v19
	v_cvt_pk_bf16_f32 v166, v20, v21
	v_cvt_pk_bf16_f32 v167, v22, v23
	s_nop 1
	v_permlane32_swap_b32_e32 v164, v166
	v_permlane32_swap_b32_e32 v165, v167
	global_store_dwordx4 v13, v[164:167], s[44:45] offset:0
	v_cvt_pk_bf16_f32 v168, v24, v25
	v_cvt_pk_bf16_f32 v169, v26, v27
	v_cvt_pk_bf16_f32 v170, v28, v29
	v_cvt_pk_bf16_f32 v171, v30, v31
	s_nop 1
	v_permlane32_swap_b32_e32 v168, v170
	v_permlane32_swap_b32_e32 v169, v171
	global_store_dwordx4 v13, v[168:171], s[44:45] offset:32
	v_cvt_pk_bf16_f32 v164, v32, v33
	v_cvt_pk_bf16_f32 v165, v34, v35
	v_cvt_pk_bf16_f32 v166, v36, v37
	v_cvt_pk_bf16_f32 v167, v38, v39
	s_nop 1
	v_permlane32_swap_b32_e32 v164, v166
	v_permlane32_swap_b32_e32 v165, v167
	global_store_dwordx4 v13, v[164:167], s[44:45] offset:64
	v_cvt_pk_bf16_f32 v168, v40, v41
	v_cvt_pk_bf16_f32 v169, v42, v43
	v_cvt_pk_bf16_f32 v170, v44, v45
	v_cvt_pk_bf16_f32 v171, v46, v47
	s_nop 1
	v_permlane32_swap_b32_e32 v168, v170
	v_permlane32_swap_b32_e32 v169, v171
	global_store_dwordx4 v13, v[168:171], s[44:45] offset:96
	v_mov_b32_e32 v212, v211
	v_mov_b32_e32 v172, v211
	s_nop 1
	v_permlane32_swap_b32_e32 v212, v172
	v_add_f32_e32 v172, v212, v172
	v_rcp_f32_e32 v172, v172
	s_nop 0
	v_mul_f32_e32 v48, v48, v172
	v_mul_f32_e32 v49, v49, v172
	v_mul_f32_e32 v50, v50, v172
	v_mul_f32_e32 v51, v51, v172
	v_mul_f32_e32 v52, v52, v172
	v_mul_f32_e32 v53, v53, v172
	v_mul_f32_e32 v54, v54, v172
	v_mul_f32_e32 v55, v55, v172
	v_mul_f32_e32 v56, v56, v172
	v_mul_f32_e32 v57, v57, v172
	v_mul_f32_e32 v58, v58, v172
	v_mul_f32_e32 v59, v59, v172
	v_mul_f32_e32 v60, v60, v172
	v_mul_f32_e32 v61, v61, v172
	v_mul_f32_e32 v62, v62, v172
	v_mul_f32_e32 v63, v63, v172
	v_mul_f32_e32 v64, v64, v172
	v_mul_f32_e32 v65, v65, v172
	v_mul_f32_e32 v66, v66, v172
	v_mul_f32_e32 v67, v67, v172
	v_mul_f32_e32 v68, v68, v172
	v_mul_f32_e32 v69, v69, v172
	v_mul_f32_e32 v70, v70, v172
	v_mul_f32_e32 v71, v71, v172
	v_mul_f32_e32 v72, v72, v172
	v_mul_f32_e32 v73, v73, v172
	v_mul_f32_e32 v74, v74, v172
	v_mul_f32_e32 v75, v75, v172
	v_mul_f32_e32 v76, v76, v172
	v_mul_f32_e32 v77, v77, v172
	v_mul_f32_e32 v78, v78, v172
	v_mul_f32_e32 v79, v79, v172
	v_cvt_pk_bf16_f32 v164, v48, v49
	v_cvt_pk_bf16_f32 v165, v50, v51
	v_cvt_pk_bf16_f32 v166, v52, v53
	v_cvt_pk_bf16_f32 v167, v54, v55
	s_nop 1
	v_permlane32_swap_b32_e32 v164, v166
	v_permlane32_swap_b32_e32 v165, v167
	global_store_dwordx4 v14, v[164:167], s[44:45] offset:0
	v_cvt_pk_bf16_f32 v168, v56, v57
	v_cvt_pk_bf16_f32 v169, v58, v59
	v_cvt_pk_bf16_f32 v170, v60, v61
	v_cvt_pk_bf16_f32 v171, v62, v63
	s_nop 1
	v_permlane32_swap_b32_e32 v168, v170
	v_permlane32_swap_b32_e32 v169, v171
	global_store_dwordx4 v14, v[168:171], s[44:45] offset:32
	v_cvt_pk_bf16_f32 v164, v64, v65
	v_cvt_pk_bf16_f32 v165, v66, v67
	v_cvt_pk_bf16_f32 v166, v68, v69
	v_cvt_pk_bf16_f32 v167, v70, v71
	s_nop 1
	v_permlane32_swap_b32_e32 v164, v166
	v_permlane32_swap_b32_e32 v165, v167
	global_store_dwordx4 v14, v[164:167], s[44:45] offset:64
	v_cvt_pk_bf16_f32 v168, v72, v73
	v_cvt_pk_bf16_f32 v169, v74, v75
	v_cvt_pk_bf16_f32 v170, v76, v77
	v_cvt_pk_bf16_f32 v171, v78, v79
	s_nop 1
	v_permlane32_swap_b32_e32 v168, v170
	v_permlane32_swap_b32_e32 v169, v171
	global_store_dwordx4 v14, v[168:171], s[44:45] offset:96
.Lat_nextunit:
	s_add_u32 s52, s52, s59
	s_cmpk_lt_i32 s52, 0x400
	s_cbranch_scc1 .Lat_unit
.Lat_exit:
	s_waitcnt vmcnt(0)
.LBB0_382:
	v_readlane_b32 s60, v254, 24
	v_readlane_b32 s62, v254, 27
	v_readlane_b32 s46, v254, 29
	v_readlane_b32 s48, v254, 31
	v_readlane_b32 s50, v254, 33
	v_readlane_b32 s52, v254, 35
	v_readlane_b32 s54, v254, 37
	v_readlane_b32 s56, v254, 39
	v_readlane_b32 s64, v254, 41
	v_readlane_b32 s68, v254, 43
	v_readlane_b32 s70, v254, 45
	v_readlane_b32 s72, v254, 47
	v_readlane_b32 s74, v254, 49
	v_readlane_b32 s84, v254, 52
	v_readlane_b32 s88, v254, 54
	v_readlane_b32 s96, v255, 7
	v_readlane_b32 s61, v254, 25
	v_readlane_b32 s59, v254, 26
	v_readlane_b32 s63, v254, 28
	v_readlane_b32 s47, v254, 30
	v_readlane_b32 s49, v254, 32
	v_readlane_b32 s51, v254, 34
	v_readlane_b32 s53, v254, 36
	v_readlane_b32 s55, v254, 38
	v_readlane_b32 s57, v254, 40
	v_readlane_b32 s65, v254, 42
	v_readlane_b32 s69, v254, 44
	v_readlane_b32 s71, v254, 46
	v_readlane_b32 s73, v254, 48
	v_readlane_b32 s75, v254, 50
	s_mov_b32 s58, 0xbfb8aa3b
	s_mov_b32 s77, 0x800000
	s_movk_i32 s67, 0x4000
	s_mov_b32 s78, 0x8000
	s_mov_b32 s79, 0xc000
	s_mov_b32 s80, 0xfffff
	s_mov_b32 s81, 0x3f317217
	s_mov_b32 s82, 0x7f800000
	v_readlane_b32 s85, v254, 53
	v_readlane_b32 s86, v255, 0
	v_readlane_b32 s89, v254, 55
	v_readlane_b32 s90, v254, 56
	v_readlane_b32 s91, v254, 57
	v_readlane_b32 s92, v254, 58
	v_readlane_b32 s93, v254, 59
	v_readlane_b32 s94, v254, 60
	v_readlane_b32 s95, v254, 61
	v_readlane_b32 s97, v255, 8
	v_readlane_b32 s98, v255, 9
	v_readlane_b32 s99, v255, 10
	v_readlane_b32 s42, v255, 11
	v_readlane_b32 s87, v255, 1
	v_readlane_b32 s43, v255, 12
